# scan: per-step wait moved one slot later (both v*k products after it, o add before it)
# speedup vs baseline: 1.0012x; 1.0003x over previous
.LBB0_685:
	ds_read_b128 v[164:167], v5 offset:0
	ds_read_b128 v[168:171], v5 offset:256
	ds_read_b128 v[172:175], v5 offset:512
	ds_read_b128 v[176:179], v5 offset:768
	ds_read_b128 v[180:183], v5 offset:1024
	ds_read_b32 v184, v9 offset:0
	ds_read_b128 v[186:189], v5 offset:1536
	ds_read_b128 v[190:193], v5 offset:1792
	ds_read_b128 v[194:197], v5 offset:2048
	ds_read_b128 v[198:201], v5 offset:2304
	ds_read_b128 v[202:205], v5 offset:2560
	ds_read_b32 v206, v9 offset:1536
	ds_read_b128 v[208:211], v5 offset:3072
	s_waitcnt lgkmcnt(12)
	v_pk_mul_f32 v[144:145], v[138:139], v[164:165]
	v_pk_fma_f32 v[144:145], v[140:141], v[166:167], v[144:145]
	v_add_f32 v146, v144, v145
	ds_read_b128 v[212:215], v5 offset:3328
	ds_read_b128 v[216:219], v5 offset:3584
	ds_read_b128 v[220:223], v5 offset:3840
	ds_read_b128 v[224:227], v5 offset:4096
	ds_read_b32 v228, v9 offset:3072
	ds_read_b128 v[230:233], v5 offset:4608
	v_add_f32_dpp v146, v146, v146 quad_perm:[1,0,3,2] row_mask:0xf bank_mask:0xf bound_ctrl:1
	s_nop 0
	s_nop 0
	v_add_f32_dpp v146, v146, v146 quad_perm:[2,3,0,1] row_mask:0xf bank_mask:0xf bound_ctrl:1
	s_nop 0
	s_waitcnt lgkmcnt(12)
	v_add_f32_dpp v146, v146, v146 row_half_mirror row_mask:0xf bank_mask:0xf bound_ctrl:1
	v_pk_mul_f32 v[176:177], v[176:177], v[184:185] op_sel_hi:[1,0]
	v_pk_mul_f32 v[178:179], v[178:179], v[184:185] op_sel_hi:[1,0]
	v_add_f32_dpp v146, v146, v146 row_mirror row_mask:0xf bank_mask:0xf bound_ctrl:1
	v_pk_fma_f32 v[176:177], v[146:147], v[168:169], v[176:177] op_sel_hi:[0,1,1] neg_lo:[1,0,0] neg_hi:[1,0,0]
	v_pk_fma_f32 v[178:179], v[146:147], v[170:171], v[178:179] op_sel_hi:[0,1,1] neg_lo:[1,0,0] neg_hi:[1,0,0]
	v_pk_fma_f32 v[138:139], v[138:139], v[172:173], v[176:177]
	v_pk_fma_f32 v[140:141], v[140:141], v[174:175], v[178:179]
	v_pk_mul_f32 v[144:145], v[138:139], v[186:187]
	v_pk_fma_f32 v[144:145], v[140:141], v[188:189], v[144:145]
	v_add_f32 v146, v144, v145
	ds_read_b128 v[234:237], v5 offset:4864
	ds_read_b128 v[238:241], v5 offset:5120
	ds_read_b128 v[242:245], v5 offset:5376
	ds_read_b128 v[246:249], v5 offset:5632
	ds_read_b32 v250, v9 offset:4608
	ds_read_b128 v[164:167], v5 offset:6144
	v_add_f32_dpp v146, v146, v146 quad_perm:[1,0,3,2] row_mask:0xf bank_mask:0xf bound_ctrl:1
	v_pk_mul_f32 v[180:181], v[138:139], v[180:181]
	v_pk_fma_f32 v[180:181], v[140:141], v[182:183], v[180:181]
	v_add_f32_dpp v146, v146, v146 quad_perm:[2,3,0,1] row_mask:0xf bank_mask:0xf bound_ctrl:1
	v_add_f32 v148, v180, v181
	s_waitcnt lgkmcnt(12)
	v_add_f32_dpp v146, v146, v146 row_half_mirror row_mask:0xf bank_mask:0xf bound_ctrl:1
	v_pk_mul_f32 v[198:199], v[198:199], v[206:207] op_sel_hi:[1,0]
	v_pk_mul_f32 v[200:201], v[200:201], v[206:207] op_sel_hi:[1,0]
	v_add_f32_dpp v146, v146, v146 row_mirror row_mask:0xf bank_mask:0xf bound_ctrl:1
	v_pk_fma_f32 v[198:199], v[146:147], v[190:191], v[198:199] op_sel_hi:[0,1,1] neg_lo:[1,0,0] neg_hi:[1,0,0]
	v_pk_fma_f32 v[200:201], v[146:147], v[192:193], v[200:201] op_sel_hi:[0,1,1] neg_lo:[1,0,0] neg_hi:[1,0,0]
	v_pk_fma_f32 v[138:139], v[138:139], v[194:195], v[198:199]
	v_pk_fma_f32 v[140:141], v[140:141], v[196:197], v[200:201]
	v_pk_mul_f32 v[144:145], v[138:139], v[208:209]
	v_pk_fma_f32 v[144:145], v[140:141], v[210:211], v[144:145]
	v_add_f32 v146, v144, v145
	ds_read_b128 v[168:171], v5 offset:6400
	ds_read_b128 v[172:175], v5 offset:6656
	ds_read_b128 v[176:179], v5 offset:6912
	ds_read_b128 v[180:183], v5 offset:7168
	ds_read_b32 v184, v9 offset:6144
	ds_read_b128 v[186:189], v5 offset:7680
	v_add_f32_dpp v146, v146, v146 quad_perm:[1,0,3,2] row_mask:0xf bank_mask:0xf bound_ctrl:1
	v_pk_mul_f32 v[202:203], v[138:139], v[202:203]
	v_pk_fma_f32 v[202:203], v[140:141], v[204:205], v[202:203]
	v_add_f32_dpp v146, v146, v146 quad_perm:[2,3,0,1] row_mask:0xf bank_mask:0xf bound_ctrl:1
	v_add_f32 v149, v202, v203
	s_waitcnt lgkmcnt(12)
	v_add_f32_dpp v146, v146, v146 row_half_mirror row_mask:0xf bank_mask:0xf bound_ctrl:1
	v_pk_mul_f32 v[220:221], v[220:221], v[228:229] op_sel_hi:[1,0]
	v_pk_mul_f32 v[222:223], v[222:223], v[228:229] op_sel_hi:[1,0]
	v_add_f32_dpp v146, v146, v146 row_mirror row_mask:0xf bank_mask:0xf bound_ctrl:1
	v_pk_fma_f32 v[220:221], v[146:147], v[212:213], v[220:221] op_sel_hi:[0,1,1] neg_lo:[1,0,0] neg_hi:[1,0,0]
	v_pk_fma_f32 v[222:223], v[146:147], v[214:215], v[222:223] op_sel_hi:[0,1,1] neg_lo:[1,0,0] neg_hi:[1,0,0]
	v_pk_fma_f32 v[138:139], v[138:139], v[216:217], v[220:221]
	v_pk_fma_f32 v[140:141], v[140:141], v[218:219], v[222:223]
	v_pk_mul_f32 v[144:145], v[138:139], v[230:231]
	v_pk_fma_f32 v[144:145], v[140:141], v[232:233], v[144:145]
	v_add_f32 v146, v144, v145
	ds_read_b128 v[190:193], v5 offset:7936
	ds_read_b128 v[194:197], v5 offset:8192
	ds_read_b128 v[198:201], v5 offset:8448
	ds_read_b128 v[202:205], v5 offset:8704
	ds_read_b32 v206, v9 offset:7680
	ds_read_b128 v[208:211], v5 offset:9216
	v_add_f32_dpp v146, v146, v146 quad_perm:[1,0,3,2] row_mask:0xf bank_mask:0xf bound_ctrl:1
	v_pk_mul_f32 v[224:225], v[138:139], v[224:225]
	v_pk_fma_f32 v[224:225], v[140:141], v[226:227], v[224:225]
	v_add_f32_dpp v146, v146, v146 quad_perm:[2,3,0,1] row_mask:0xf bank_mask:0xf bound_ctrl:1
	v_add_f32 v150, v224, v225
	s_waitcnt lgkmcnt(12)
	v_add_f32_dpp v146, v146, v146 row_half_mirror row_mask:0xf bank_mask:0xf bound_ctrl:1
	v_pk_mul_f32 v[242:243], v[242:243], v[250:251] op_sel_hi:[1,0]
	v_pk_mul_f32 v[244:245], v[244:245], v[250:251] op_sel_hi:[1,0]
	v_add_f32_dpp v146, v146, v146 row_mirror row_mask:0xf bank_mask:0xf bound_ctrl:1
	v_pk_fma_f32 v[242:243], v[146:147], v[234:235], v[242:243] op_sel_hi:[0,1,1] neg_lo:[1,0,0] neg_hi:[1,0,0]
	v_pk_fma_f32 v[244:245], v[146:147], v[236:237], v[244:245] op_sel_hi:[0,1,1] neg_lo:[1,0,0] neg_hi:[1,0,0]
	v_pk_fma_f32 v[138:139], v[138:139], v[238:239], v[242:243]
	v_pk_fma_f32 v[140:141], v[140:141], v[240:241], v[244:245]
	v_pk_mul_f32 v[144:145], v[138:139], v[164:165]
	v_pk_fma_f32 v[144:145], v[140:141], v[166:167], v[144:145]
	v_add_f32 v146, v144, v145
	ds_read_b128 v[212:215], v5 offset:9472
	ds_read_b128 v[216:219], v5 offset:9728
	ds_read_b128 v[220:223], v5 offset:9984
	ds_read_b128 v[224:227], v5 offset:10240
	ds_read_b32 v228, v9 offset:9216
	ds_read_b128 v[230:233], v5 offset:10752
	v_add_f32_dpp v146, v146, v146 quad_perm:[1,0,3,2] row_mask:0xf bank_mask:0xf bound_ctrl:1
	v_pk_mul_f32 v[246:247], v[138:139], v[246:247]
	v_pk_fma_f32 v[246:247], v[140:141], v[248:249], v[246:247]
	v_add_f32_dpp v146, v146, v146 quad_perm:[2,3,0,1] row_mask:0xf bank_mask:0xf bound_ctrl:1
	v_add_f32 v151, v246, v247
	s_waitcnt lgkmcnt(12)
	v_add_f32_dpp v146, v146, v146 row_half_mirror row_mask:0xf bank_mask:0xf bound_ctrl:1
	v_pk_mul_f32 v[176:177], v[176:177], v[184:185] op_sel_hi:[1,0]
	v_pk_mul_f32 v[178:179], v[178:179], v[184:185] op_sel_hi:[1,0]
	v_add_f32_dpp v146, v146, v146 row_mirror row_mask:0xf bank_mask:0xf bound_ctrl:1
	v_pk_fma_f32 v[176:177], v[146:147], v[168:169], v[176:177] op_sel_hi:[0,1,1] neg_lo:[1,0,0] neg_hi:[1,0,0]
	v_pk_fma_f32 v[178:179], v[146:147], v[170:171], v[178:179] op_sel_hi:[0,1,1] neg_lo:[1,0,0] neg_hi:[1,0,0]
	v_pk_fma_f32 v[138:139], v[138:139], v[172:173], v[176:177]
	v_pk_fma_f32 v[140:141], v[140:141], v[174:175], v[178:179]
	v_pk_mul_f32 v[144:145], v[138:139], v[186:187]
	v_pk_fma_f32 v[144:145], v[140:141], v[188:189], v[144:145]
	v_add_f32 v146, v144, v145
	ds_read_b128 v[234:237], v5 offset:11008
	ds_read_b128 v[238:241], v5 offset:11264
	ds_read_b128 v[242:245], v5 offset:11520
	ds_read_b128 v[246:249], v5 offset:11776
	ds_read_b32 v250, v9 offset:10752
	ds_read_b128 v[164:167], v5 offset:12288
	v_add_f32_dpp v146, v146, v146 quad_perm:[1,0,3,2] row_mask:0xf bank_mask:0xf bound_ctrl:1
	v_pk_mul_f32 v[180:181], v[138:139], v[180:181]
	v_pk_fma_f32 v[180:181], v[140:141], v[182:183], v[180:181]
	v_add_f32_dpp v146, v146, v146 quad_perm:[2,3,0,1] row_mask:0xf bank_mask:0xf bound_ctrl:1
	v_add_f32 v152, v180, v181
	s_waitcnt lgkmcnt(12)
	v_add_f32_dpp v146, v146, v146 row_half_mirror row_mask:0xf bank_mask:0xf bound_ctrl:1
	v_pk_mul_f32 v[198:199], v[198:199], v[206:207] op_sel_hi:[1,0]
	v_pk_mul_f32 v[200:201], v[200:201], v[206:207] op_sel_hi:[1,0]
	v_add_f32_dpp v146, v146, v146 row_mirror row_mask:0xf bank_mask:0xf bound_ctrl:1
	v_pk_fma_f32 v[198:199], v[146:147], v[190:191], v[198:199] op_sel_hi:[0,1,1] neg_lo:[1,0,0] neg_hi:[1,0,0]
	v_pk_fma_f32 v[200:201], v[146:147], v[192:193], v[200:201] op_sel_hi:[0,1,1] neg_lo:[1,0,0] neg_hi:[1,0,0]
	v_pk_fma_f32 v[138:139], v[138:139], v[194:195], v[198:199]
	v_pk_fma_f32 v[140:141], v[140:141], v[196:197], v[200:201]
	v_pk_mul_f32 v[144:145], v[138:139], v[208:209]
	v_pk_fma_f32 v[144:145], v[140:141], v[210:211], v[144:145]
	v_add_f32 v146, v144, v145
	ds_read_b128 v[168:171], v5 offset:12544
	ds_read_b128 v[172:175], v5 offset:12800
	ds_read_b128 v[176:179], v5 offset:13056
	ds_read_b128 v[180:183], v5 offset:13312
	ds_read_b32 v184, v9 offset:12288
	ds_read_b128 v[186:189], v5 offset:13824
	v_add_f32_dpp v146, v146, v146 quad_perm:[1,0,3,2] row_mask:0xf bank_mask:0xf bound_ctrl:1
	v_pk_mul_f32 v[202:203], v[138:139], v[202:203]
	v_pk_fma_f32 v[202:203], v[140:141], v[204:205], v[202:203]
	v_add_f32_dpp v146, v146, v146 quad_perm:[2,3,0,1] row_mask:0xf bank_mask:0xf bound_ctrl:1
	v_add_f32 v153, v202, v203
	s_waitcnt lgkmcnt(12)
	v_add_f32_dpp v146, v146, v146 row_half_mirror row_mask:0xf bank_mask:0xf bound_ctrl:1
	v_pk_mul_f32 v[220:221], v[220:221], v[228:229] op_sel_hi:[1,0]
	v_pk_mul_f32 v[222:223], v[222:223], v[228:229] op_sel_hi:[1,0]
	v_add_f32_dpp v146, v146, v146 row_mirror row_mask:0xf bank_mask:0xf bound_ctrl:1
	v_pk_fma_f32 v[220:221], v[146:147], v[212:213], v[220:221] op_sel_hi:[0,1,1] neg_lo:[1,0,0] neg_hi:[1,0,0]
	v_pk_fma_f32 v[222:223], v[146:147], v[214:215], v[222:223] op_sel_hi:[0,1,1] neg_lo:[1,0,0] neg_hi:[1,0,0]
	v_pk_fma_f32 v[138:139], v[138:139], v[216:217], v[220:221]
	v_pk_fma_f32 v[140:141], v[140:141], v[218:219], v[222:223]
	v_pk_mul_f32 v[144:145], v[138:139], v[230:231]
	v_pk_fma_f32 v[144:145], v[140:141], v[232:233], v[144:145]
	v_add_f32 v146, v144, v145
	ds_read_b128 v[190:193], v5 offset:14080
	ds_read_b128 v[194:197], v5 offset:14336
	ds_read_b128 v[198:201], v5 offset:14592
	ds_read_b128 v[202:205], v5 offset:14848
	ds_read_b32 v206, v9 offset:13824
	ds_read_b128 v[208:211], v5 offset:15360
	v_add_f32_dpp v146, v146, v146 quad_perm:[1,0,3,2] row_mask:0xf bank_mask:0xf bound_ctrl:1
	v_pk_mul_f32 v[224:225], v[138:139], v[224:225]
	v_pk_fma_f32 v[224:225], v[140:141], v[226:227], v[224:225]
	v_add_f32_dpp v146, v146, v146 quad_perm:[2,3,0,1] row_mask:0xf bank_mask:0xf bound_ctrl:1
	v_add_f32 v154, v224, v225
	s_waitcnt lgkmcnt(12)
	v_add_f32_dpp v146, v146, v146 row_half_mirror row_mask:0xf bank_mask:0xf bound_ctrl:1
	v_pk_mul_f32 v[242:243], v[242:243], v[250:251] op_sel_hi:[1,0]
	v_pk_mul_f32 v[244:245], v[244:245], v[250:251] op_sel_hi:[1,0]
	v_add_f32_dpp v146, v146, v146 row_mirror row_mask:0xf bank_mask:0xf bound_ctrl:1
	v_pk_fma_f32 v[242:243], v[146:147], v[234:235], v[242:243] op_sel_hi:[0,1,1] neg_lo:[1,0,0] neg_hi:[1,0,0]
	v_pk_fma_f32 v[244:245], v[146:147], v[236:237], v[244:245] op_sel_hi:[0,1,1] neg_lo:[1,0,0] neg_hi:[1,0,0]
	v_pk_fma_f32 v[138:139], v[138:139], v[238:239], v[242:243]
	v_pk_fma_f32 v[140:141], v[140:141], v[240:241], v[244:245]
	v_pk_mul_f32 v[144:145], v[138:139], v[164:165]
	v_pk_fma_f32 v[144:145], v[140:141], v[166:167], v[144:145]
	v_add_f32 v146, v144, v145
	ds_read_b128 v[212:215], v5 offset:15616
	ds_read_b128 v[216:219], v5 offset:15872
	ds_read_b128 v[220:223], v5 offset:16128
	ds_read_b128 v[224:227], v5 offset:16384
	ds_read_b32 v228, v9 offset:15360
	ds_read_b128 v[230:233], v5 offset:16896
	v_add_f32_dpp v146, v146, v146 quad_perm:[1,0,3,2] row_mask:0xf bank_mask:0xf bound_ctrl:1
	v_pk_mul_f32 v[246:247], v[138:139], v[246:247]
	v_pk_fma_f32 v[246:247], v[140:141], v[248:249], v[246:247]
	v_add_f32_dpp v146, v146, v146 quad_perm:[2,3,0,1] row_mask:0xf bank_mask:0xf bound_ctrl:1
	v_add_f32 v155, v246, v247
	s_waitcnt lgkmcnt(12)
	v_add_f32_dpp v146, v146, v146 row_half_mirror row_mask:0xf bank_mask:0xf bound_ctrl:1
	v_pk_mul_f32 v[176:177], v[176:177], v[184:185] op_sel_hi:[1,0]
	v_pk_mul_f32 v[178:179], v[178:179], v[184:185] op_sel_hi:[1,0]
	v_add_f32_dpp v146, v146, v146 row_mirror row_mask:0xf bank_mask:0xf bound_ctrl:1
	v_pk_fma_f32 v[176:177], v[146:147], v[168:169], v[176:177] op_sel_hi:[0,1,1] neg_lo:[1,0,0] neg_hi:[1,0,0]
	v_pk_fma_f32 v[178:179], v[146:147], v[170:171], v[178:179] op_sel_hi:[0,1,1] neg_lo:[1,0,0] neg_hi:[1,0,0]
	v_pk_fma_f32 v[138:139], v[138:139], v[172:173], v[176:177]
	v_pk_fma_f32 v[140:141], v[140:141], v[174:175], v[178:179]
	v_pk_mul_f32 v[144:145], v[138:139], v[186:187]
	v_pk_fma_f32 v[144:145], v[140:141], v[188:189], v[144:145]
	v_add_f32 v146, v144, v145
	ds_read_b128 v[234:237], v5 offset:17152
	ds_read_b128 v[238:241], v5 offset:17408
	ds_read_b128 v[242:245], v5 offset:17664
	ds_read_b128 v[246:249], v5 offset:17920
	ds_read_b32 v250, v9 offset:16896
	ds_read_b128 v[164:167], v5 offset:18432
	v_add_f32_dpp v146, v146, v146 quad_perm:[1,0,3,2] row_mask:0xf bank_mask:0xf bound_ctrl:1
	v_pk_mul_f32 v[180:181], v[138:139], v[180:181]
	v_pk_fma_f32 v[180:181], v[140:141], v[182:183], v[180:181]
	v_add_f32_dpp v146, v146, v146 quad_perm:[2,3,0,1] row_mask:0xf bank_mask:0xf bound_ctrl:1
	v_add_f32 v156, v180, v181
	s_waitcnt lgkmcnt(12)
	v_add_f32_dpp v146, v146, v146 row_half_mirror row_mask:0xf bank_mask:0xf bound_ctrl:1
	v_pk_mul_f32 v[198:199], v[198:199], v[206:207] op_sel_hi:[1,0]
	v_pk_mul_f32 v[200:201], v[200:201], v[206:207] op_sel_hi:[1,0]
	v_add_f32_dpp v146, v146, v146 row_mirror row_mask:0xf bank_mask:0xf bound_ctrl:1
	v_pk_fma_f32 v[198:199], v[146:147], v[190:191], v[198:199] op_sel_hi:[0,1,1] neg_lo:[1,0,0] neg_hi:[1,0,0]
	v_pk_fma_f32 v[200:201], v[146:147], v[192:193], v[200:201] op_sel_hi:[0,1,1] neg_lo:[1,0,0] neg_hi:[1,0,0]
	v_pk_fma_f32 v[138:139], v[138:139], v[194:195], v[198:199]
	v_pk_fma_f32 v[140:141], v[140:141], v[196:197], v[200:201]
	v_pk_mul_f32 v[144:145], v[138:139], v[208:209]
	v_pk_fma_f32 v[144:145], v[140:141], v[210:211], v[144:145]
	v_add_f32 v146, v144, v145
	ds_read_b128 v[168:171], v5 offset:18688
	ds_read_b128 v[172:175], v5 offset:18944
	ds_read_b128 v[176:179], v5 offset:19200
	ds_read_b128 v[180:183], v5 offset:19456
	ds_read_b32 v184, v9 offset:18432
	ds_read_b128 v[186:189], v5 offset:19968
	v_add_f32_dpp v146, v146, v146 quad_perm:[1,0,3,2] row_mask:0xf bank_mask:0xf bound_ctrl:1
	v_pk_mul_f32 v[202:203], v[138:139], v[202:203]
	v_pk_fma_f32 v[202:203], v[140:141], v[204:205], v[202:203]
	v_add_f32_dpp v146, v146, v146 quad_perm:[2,3,0,1] row_mask:0xf bank_mask:0xf bound_ctrl:1
	v_add_f32 v157, v202, v203
	s_waitcnt lgkmcnt(12)
	v_add_f32_dpp v146, v146, v146 row_half_mirror row_mask:0xf bank_mask:0xf bound_ctrl:1
	v_pk_mul_f32 v[220:221], v[220:221], v[228:229] op_sel_hi:[1,0]
	v_pk_mul_f32 v[222:223], v[222:223], v[228:229] op_sel_hi:[1,0]
	v_add_f32_dpp v146, v146, v146 row_mirror row_mask:0xf bank_mask:0xf bound_ctrl:1
	v_pk_fma_f32 v[220:221], v[146:147], v[212:213], v[220:221] op_sel_hi:[0,1,1] neg_lo:[1,0,0] neg_hi:[1,0,0]
	v_pk_fma_f32 v[222:223], v[146:147], v[214:215], v[222:223] op_sel_hi:[0,1,1] neg_lo:[1,0,0] neg_hi:[1,0,0]
	v_pk_fma_f32 v[138:139], v[138:139], v[216:217], v[220:221]
	v_pk_fma_f32 v[140:141], v[140:141], v[218:219], v[222:223]
	v_pk_mul_f32 v[144:145], v[138:139], v[230:231]
	v_pk_fma_f32 v[144:145], v[140:141], v[232:233], v[144:145]
	v_add_f32 v146, v144, v145
	ds_read_b128 v[190:193], v5 offset:20224
	ds_read_b128 v[194:197], v5 offset:20480
	ds_read_b128 v[198:201], v5 offset:20736
	ds_read_b128 v[202:205], v5 offset:20992
	ds_read_b32 v206, v9 offset:19968
	ds_read_b128 v[208:211], v5 offset:21504
	v_add_f32_dpp v146, v146, v146 quad_perm:[1,0,3,2] row_mask:0xf bank_mask:0xf bound_ctrl:1
	v_pk_mul_f32 v[224:225], v[138:139], v[224:225]
	v_pk_fma_f32 v[224:225], v[140:141], v[226:227], v[224:225]
	v_add_f32_dpp v146, v146, v146 quad_perm:[2,3,0,1] row_mask:0xf bank_mask:0xf bound_ctrl:1
	v_add_f32 v158, v224, v225
	s_waitcnt lgkmcnt(12)
	v_add_f32_dpp v146, v146, v146 row_half_mirror row_mask:0xf bank_mask:0xf bound_ctrl:1
	v_pk_mul_f32 v[242:243], v[242:243], v[250:251] op_sel_hi:[1,0]
	v_pk_mul_f32 v[244:245], v[244:245], v[250:251] op_sel_hi:[1,0]
	v_add_f32_dpp v146, v146, v146 row_mirror row_mask:0xf bank_mask:0xf bound_ctrl:1
	v_pk_fma_f32 v[242:243], v[146:147], v[234:235], v[242:243] op_sel_hi:[0,1,1] neg_lo:[1,0,0] neg_hi:[1,0,0]
	v_pk_fma_f32 v[244:245], v[146:147], v[236:237], v[244:245] op_sel_hi:[0,1,1] neg_lo:[1,0,0] neg_hi:[1,0,0]
	v_pk_fma_f32 v[138:139], v[138:139], v[238:239], v[242:243]
	v_pk_fma_f32 v[140:141], v[140:141], v[240:241], v[244:245]
	v_pk_mul_f32 v[144:145], v[138:139], v[164:165]
	v_pk_fma_f32 v[144:145], v[140:141], v[166:167], v[144:145]
	v_add_f32 v146, v144, v145
	ds_read_b128 v[212:215], v5 offset:21760
	ds_read_b128 v[216:219], v5 offset:22016
	ds_read_b128 v[220:223], v5 offset:22272
	ds_read_b128 v[224:227], v5 offset:22528
	ds_read_b32 v228, v9 offset:21504
	ds_read_b128 v[230:233], v5 offset:23040
	v_add_f32_dpp v146, v146, v146 quad_perm:[1,0,3,2] row_mask:0xf bank_mask:0xf bound_ctrl:1
	v_pk_mul_f32 v[246:247], v[138:139], v[246:247]
	v_pk_fma_f32 v[246:247], v[140:141], v[248:249], v[246:247]
	v_add_f32_dpp v146, v146, v146 quad_perm:[2,3,0,1] row_mask:0xf bank_mask:0xf bound_ctrl:1
	v_add_f32 v159, v246, v247
	s_waitcnt lgkmcnt(12)
	v_add_f32_dpp v146, v146, v146 row_half_mirror row_mask:0xf bank_mask:0xf bound_ctrl:1
	v_pk_mul_f32 v[176:177], v[176:177], v[184:185] op_sel_hi:[1,0]
	v_pk_mul_f32 v[178:179], v[178:179], v[184:185] op_sel_hi:[1,0]
	v_add_f32_dpp v146, v146, v146 row_mirror row_mask:0xf bank_mask:0xf bound_ctrl:1
	v_pk_fma_f32 v[176:177], v[146:147], v[168:169], v[176:177] op_sel_hi:[0,1,1] neg_lo:[1,0,0] neg_hi:[1,0,0]
	v_pk_fma_f32 v[178:179], v[146:147], v[170:171], v[178:179] op_sel_hi:[0,1,1] neg_lo:[1,0,0] neg_hi:[1,0,0]
	v_pk_fma_f32 v[138:139], v[138:139], v[172:173], v[176:177]
	v_pk_fma_f32 v[140:141], v[140:141], v[174:175], v[178:179]
	v_pk_mul_f32 v[144:145], v[138:139], v[186:187]
	v_pk_fma_f32 v[144:145], v[140:141], v[188:189], v[144:145]
	v_add_f32 v146, v144, v145
	ds_read_b128 v[234:237], v5 offset:23296
	ds_read_b128 v[238:241], v5 offset:23552
	ds_read_b128 v[242:245], v5 offset:23808
	ds_read_b128 v[246:249], v5 offset:24064
	ds_read_b32 v250, v9 offset:23040
	ds_read_b128 v[164:167], v5 offset:24576
	v_add_f32_dpp v146, v146, v146 quad_perm:[1,0,3,2] row_mask:0xf bank_mask:0xf bound_ctrl:1
	v_pk_mul_f32 v[180:181], v[138:139], v[180:181]
	v_pk_fma_f32 v[180:181], v[140:141], v[182:183], v[180:181]
	v_add_f32_dpp v146, v146, v146 quad_perm:[2,3,0,1] row_mask:0xf bank_mask:0xf bound_ctrl:1
	v_add_f32 v160, v180, v181
	s_waitcnt lgkmcnt(12)
	v_add_f32_dpp v146, v146, v146 row_half_mirror row_mask:0xf bank_mask:0xf bound_ctrl:1
	v_pk_mul_f32 v[198:199], v[198:199], v[206:207] op_sel_hi:[1,0]
	v_pk_mul_f32 v[200:201], v[200:201], v[206:207] op_sel_hi:[1,0]
	v_add_f32_dpp v146, v146, v146 row_mirror row_mask:0xf bank_mask:0xf bound_ctrl:1
	v_pk_fma_f32 v[198:199], v[146:147], v[190:191], v[198:199] op_sel_hi:[0,1,1] neg_lo:[1,0,0] neg_hi:[1,0,0]
	v_pk_fma_f32 v[200:201], v[146:147], v[192:193], v[200:201] op_sel_hi:[0,1,1] neg_lo:[1,0,0] neg_hi:[1,0,0]
	v_pk_fma_f32 v[138:139], v[138:139], v[194:195], v[198:199]
	v_pk_fma_f32 v[140:141], v[140:141], v[196:197], v[200:201]
	v_pk_mul_f32 v[144:145], v[138:139], v[208:209]
	v_pk_fma_f32 v[144:145], v[140:141], v[210:211], v[144:145]
	v_add_f32 v146, v144, v145
	ds_read_b128 v[168:171], v5 offset:24832
	ds_read_b128 v[172:175], v5 offset:25088
	ds_read_b128 v[176:179], v5 offset:25344
	ds_read_b128 v[180:183], v5 offset:25600
	ds_read_b32 v184, v9 offset:24576
	ds_read_b128 v[186:189], v5 offset:26112
	v_add_f32_dpp v146, v146, v146 quad_perm:[1,0,3,2] row_mask:0xf bank_mask:0xf bound_ctrl:1
	v_pk_mul_f32 v[202:203], v[138:139], v[202:203]
	v_pk_fma_f32 v[202:203], v[140:141], v[204:205], v[202:203]
	v_add_f32_dpp v146, v146, v146 quad_perm:[2,3,0,1] row_mask:0xf bank_mask:0xf bound_ctrl:1
	v_add_f32 v161, v202, v203
	s_waitcnt lgkmcnt(12)
	v_add_f32_dpp v146, v146, v146 row_half_mirror row_mask:0xf bank_mask:0xf bound_ctrl:1
	v_pk_mul_f32 v[220:221], v[220:221], v[228:229] op_sel_hi:[1,0]
	v_pk_mul_f32 v[222:223], v[222:223], v[228:229] op_sel_hi:[1,0]
	v_add_f32_dpp v146, v146, v146 row_mirror row_mask:0xf bank_mask:0xf bound_ctrl:1
	v_pk_fma_f32 v[220:221], v[146:147], v[212:213], v[220:221] op_sel_hi:[0,1,1] neg_lo:[1,0,0] neg_hi:[1,0,0]
	v_pk_fma_f32 v[222:223], v[146:147], v[214:215], v[222:223] op_sel_hi:[0,1,1] neg_lo:[1,0,0] neg_hi:[1,0,0]
	v_pk_fma_f32 v[138:139], v[138:139], v[216:217], v[220:221]
	v_pk_fma_f32 v[140:141], v[140:141], v[218:219], v[222:223]
	v_pk_mul_f32 v[144:145], v[138:139], v[230:231]
	v_pk_fma_f32 v[144:145], v[140:141], v[232:233], v[144:145]
	v_add_f32 v146, v144, v145
	ds_read_b128 v[190:193], v5 offset:26368
	ds_read_b128 v[194:197], v5 offset:26624
	ds_read_b128 v[198:201], v5 offset:26880
	ds_read_b128 v[202:205], v5 offset:27136
	ds_read_b32 v206, v9 offset:26112
	ds_read_b128 v[208:211], v5 offset:27648
	v_add_f32_dpp v146, v146, v146 quad_perm:[1,0,3,2] row_mask:0xf bank_mask:0xf bound_ctrl:1
	v_pk_mul_f32 v[224:225], v[138:139], v[224:225]
	v_pk_fma_f32 v[224:225], v[140:141], v[226:227], v[224:225]
	v_add_f32_dpp v146, v146, v146 quad_perm:[2,3,0,1] row_mask:0xf bank_mask:0xf bound_ctrl:1
	v_add_f32 v162, v224, v225
	s_waitcnt lgkmcnt(12)
	v_add_f32_dpp v146, v146, v146 row_half_mirror row_mask:0xf bank_mask:0xf bound_ctrl:1
	v_pk_mul_f32 v[242:243], v[242:243], v[250:251] op_sel_hi:[1,0]
	v_pk_mul_f32 v[244:245], v[244:245], v[250:251] op_sel_hi:[1,0]
	v_add_f32_dpp v146, v146, v146 row_mirror row_mask:0xf bank_mask:0xf bound_ctrl:1
	v_pk_fma_f32 v[242:243], v[146:147], v[234:235], v[242:243] op_sel_hi:[0,1,1] neg_lo:[1,0,0] neg_hi:[1,0,0]
	v_pk_fma_f32 v[244:245], v[146:147], v[236:237], v[244:245] op_sel_hi:[0,1,1] neg_lo:[1,0,0] neg_hi:[1,0,0]
	v_pk_fma_f32 v[138:139], v[138:139], v[238:239], v[242:243]
	v_pk_fma_f32 v[140:141], v[140:141], v[240:241], v[244:245]
	v_pk_mul_f32 v[144:145], v[138:139], v[164:165]
	v_pk_fma_f32 v[144:145], v[140:141], v[166:167], v[144:145]
	v_add_f32 v146, v144, v145
	ds_read_b128 v[212:215], v5 offset:27904
	ds_read_b128 v[216:219], v5 offset:28160
	ds_read_b128 v[220:223], v5 offset:28416
	ds_read_b128 v[224:227], v5 offset:28672
	ds_read_b32 v228, v9 offset:27648
	ds_read_b128 v[230:233], v5 offset:29184
	v_add_f32_dpp v146, v146, v146 quad_perm:[1,0,3,2] row_mask:0xf bank_mask:0xf bound_ctrl:1
	v_pk_mul_f32 v[246:247], v[138:139], v[246:247]
	v_pk_fma_f32 v[246:247], v[140:141], v[248:249], v[246:247]
	v_add_f32_dpp v146, v146, v146 quad_perm:[2,3,0,1] row_mask:0xf bank_mask:0xf bound_ctrl:1
	v_add_f32 v163, v246, v247
	s_waitcnt lgkmcnt(12)
	v_add_f32_dpp v146, v146, v146 row_half_mirror row_mask:0xf bank_mask:0xf bound_ctrl:1
	v_pk_mul_f32 v[176:177], v[176:177], v[184:185] op_sel_hi:[1,0]
	v_pk_mul_f32 v[178:179], v[178:179], v[184:185] op_sel_hi:[1,0]
	v_add_f32_dpp v146, v146, v146 row_mirror row_mask:0xf bank_mask:0xf bound_ctrl:1
	v_pk_fma_f32 v[176:177], v[146:147], v[168:169], v[176:177] op_sel_hi:[0,1,1] neg_lo:[1,0,0] neg_hi:[1,0,0]
	v_pk_fma_f32 v[178:179], v[146:147], v[170:171], v[178:179] op_sel_hi:[0,1,1] neg_lo:[1,0,0] neg_hi:[1,0,0]
	v_pk_fma_f32 v[138:139], v[138:139], v[172:173], v[176:177]
	v_pk_fma_f32 v[140:141], v[140:141], v[174:175], v[178:179]
	v_pk_mul_f32 v[144:145], v[138:139], v[186:187]
	v_pk_fma_f32 v[144:145], v[140:141], v[188:189], v[144:145]
	v_add_f32 v146, v144, v145
	v_add_f32_dpp v102, v148, v148 row_mirror row_mask:0xf bank_mask:0x3 bound_ctrl:1
	v_add_f32_dpp v102, v156, v156 row_mirror row_mask:0xf bank_mask:0xc bound_ctrl:1
	v_add_f32_dpp v103, v149, v149 row_mirror row_mask:0xf bank_mask:0x3 bound_ctrl:1
	v_add_f32_dpp v103, v157, v157 row_mirror row_mask:0xf bank_mask:0xc bound_ctrl:1
	v_add_f32_dpp v104, v150, v150 row_mirror row_mask:0xf bank_mask:0x3 bound_ctrl:1
	v_add_f32_dpp v104, v158, v158 row_mirror row_mask:0xf bank_mask:0xc bound_ctrl:1
	v_add_f32_dpp v105, v151, v151 row_mirror row_mask:0xf bank_mask:0x3 bound_ctrl:1
	v_add_f32_dpp v105, v159, v159 row_mirror row_mask:0xf bank_mask:0xc bound_ctrl:1
	v_add_f32_dpp v106, v152, v152 row_mirror row_mask:0xf bank_mask:0x3 bound_ctrl:1
	v_add_f32_dpp v106, v160, v160 row_mirror row_mask:0xf bank_mask:0xc bound_ctrl:1
	v_add_f32_dpp v107, v153, v153 row_mirror row_mask:0xf bank_mask:0x3 bound_ctrl:1
	v_add_f32_dpp v107, v161, v161 row_mirror row_mask:0xf bank_mask:0xc bound_ctrl:1
	v_add_f32_dpp v108, v154, v154 row_mirror row_mask:0xf bank_mask:0x3 bound_ctrl:1
	v_add_f32_dpp v108, v162, v162 row_mirror row_mask:0xf bank_mask:0xc bound_ctrl:1
	v_add_f32_dpp v109, v155, v155 row_mirror row_mask:0xf bank_mask:0x3 bound_ctrl:1
	v_add_f32_dpp v109, v163, v163 row_mirror row_mask:0xf bank_mask:0xc bound_ctrl:1
	v_add_f32_dpp v110, v102, v102 row_half_mirror row_mask:0xf bank_mask:0x5 bound_ctrl:1
	v_add_f32_dpp v110, v106, v106 row_half_mirror row_mask:0xf bank_mask:0xa bound_ctrl:1
	v_add_f32_dpp v111, v103, v103 row_half_mirror row_mask:0xf bank_mask:0x5 bound_ctrl:1
	v_add_f32_dpp v111, v107, v107 row_half_mirror row_mask:0xf bank_mask:0xa bound_ctrl:1
	v_add_f32_dpp v112, v104, v104 row_half_mirror row_mask:0xf bank_mask:0x5 bound_ctrl:1
	v_add_f32_dpp v112, v108, v108 row_half_mirror row_mask:0xf bank_mask:0xa bound_ctrl:1
	v_add_f32_dpp v113, v105, v105 row_half_mirror row_mask:0xf bank_mask:0x5 bound_ctrl:1
	v_add_f32_dpp v113, v109, v109 row_half_mirror row_mask:0xf bank_mask:0xa bound_ctrl:1
	s_mov_b32 vcc_lo, 0xcccccccc
	s_mov_b32 vcc_hi, 0xcccccccc
	v_cndmask_b32 v116, v112, v110, vcc
	v_cndmask_b32 v117, v113, v111, vcc
	v_cndmask_b32 v114, v110, v112, vcc
	v_cndmask_b32 v115, v111, v113, vcc
	v_add_f32_dpp v114, v116, v114 quad_perm:[2,3,0,1] row_mask:0xf bank_mask:0xf bound_ctrl:1
	v_add_f32_dpp v115, v117, v115 quad_perm:[2,3,0,1] row_mask:0xf bank_mask:0xf bound_ctrl:1
	s_mov_b32 vcc_lo, 0xaaaaaaaa
	s_mov_b32 vcc_hi, 0xaaaaaaaa
	v_cndmask_b32 v116, v115, v114, vcc
	v_cndmask_b32 v117, v114, v115, vcc
	s_nop 0
	v_add_f32_dpp v18, v116, v117 quad_perm:[1,0,3,2] row_mask:0xf bank_mask:0xf bound_ctrl:1
	ds_read_b128 v[234:237], v5 offset:29440
	ds_read_b128 v[238:241], v5 offset:29696
	ds_read_b128 v[242:245], v5 offset:29952
	ds_read_b128 v[246:249], v5 offset:30208
	ds_read_b32 v250, v9 offset:29184
	ds_read_b128 v[164:167], v5 offset:30720
	v_add_f32_dpp v146, v146, v146 quad_perm:[1,0,3,2] row_mask:0xf bank_mask:0xf bound_ctrl:1
	v_pk_mul_f32 v[180:181], v[138:139], v[180:181]
	v_pk_fma_f32 v[180:181], v[140:141], v[182:183], v[180:181]
	v_add_f32_dpp v146, v146, v146 quad_perm:[2,3,0,1] row_mask:0xf bank_mask:0xf bound_ctrl:1
	v_add_f32 v148, v180, v181
	s_waitcnt lgkmcnt(12)
	v_add_f32_dpp v146, v146, v146 row_half_mirror row_mask:0xf bank_mask:0xf bound_ctrl:1
	v_pk_mul_f32 v[198:199], v[198:199], v[206:207] op_sel_hi:[1,0]
	v_pk_mul_f32 v[200:201], v[200:201], v[206:207] op_sel_hi:[1,0]
	v_add_f32_dpp v146, v146, v146 row_mirror row_mask:0xf bank_mask:0xf bound_ctrl:1
	v_pk_fma_f32 v[198:199], v[146:147], v[190:191], v[198:199] op_sel_hi:[0,1,1] neg_lo:[1,0,0] neg_hi:[1,0,0]
	v_pk_fma_f32 v[200:201], v[146:147], v[192:193], v[200:201] op_sel_hi:[0,1,1] neg_lo:[1,0,0] neg_hi:[1,0,0]
	v_pk_fma_f32 v[138:139], v[138:139], v[194:195], v[198:199]
	v_pk_fma_f32 v[140:141], v[140:141], v[196:197], v[200:201]
	v_pk_mul_f32 v[144:145], v[138:139], v[208:209]
	v_pk_fma_f32 v[144:145], v[140:141], v[210:211], v[144:145]
	v_add_f32 v146, v144, v145
	ds_read_b128 v[168:171], v5 offset:30976
	ds_read_b128 v[172:175], v5 offset:31232
	ds_read_b128 v[176:179], v5 offset:31488
	ds_read_b128 v[180:183], v5 offset:31744
	ds_read_b32 v184, v9 offset:30720
	ds_read_b128 v[186:189], v5 offset:32256
	v_add_f32_dpp v146, v146, v146 quad_perm:[1,0,3,2] row_mask:0xf bank_mask:0xf bound_ctrl:1
	v_pk_mul_f32 v[202:203], v[138:139], v[202:203]
	v_pk_fma_f32 v[202:203], v[140:141], v[204:205], v[202:203]
	v_add_f32_dpp v146, v146, v146 quad_perm:[2,3,0,1] row_mask:0xf bank_mask:0xf bound_ctrl:1
	v_add_f32 v149, v202, v203
	s_waitcnt lgkmcnt(12)
	v_add_f32_dpp v146, v146, v146 row_half_mirror row_mask:0xf bank_mask:0xf bound_ctrl:1
	v_pk_mul_f32 v[220:221], v[220:221], v[228:229] op_sel_hi:[1,0]
	v_pk_mul_f32 v[222:223], v[222:223], v[228:229] op_sel_hi:[1,0]
	v_add_f32_dpp v146, v146, v146 row_mirror row_mask:0xf bank_mask:0xf bound_ctrl:1
	v_pk_fma_f32 v[220:221], v[146:147], v[212:213], v[220:221] op_sel_hi:[0,1,1] neg_lo:[1,0,0] neg_hi:[1,0,0]
	v_pk_fma_f32 v[222:223], v[146:147], v[214:215], v[222:223] op_sel_hi:[0,1,1] neg_lo:[1,0,0] neg_hi:[1,0,0]
	v_pk_fma_f32 v[138:139], v[138:139], v[216:217], v[220:221]
	v_pk_fma_f32 v[140:141], v[140:141], v[218:219], v[222:223]
	v_pk_mul_f32 v[144:145], v[138:139], v[230:231]
	v_pk_fma_f32 v[144:145], v[140:141], v[232:233], v[144:145]
	v_add_f32 v146, v144, v145
	ds_read_b128 v[190:193], v5 offset:32512
	ds_read_b128 v[194:197], v5 offset:32768
	ds_read_b128 v[198:201], v5 offset:33024
	ds_read_b128 v[202:205], v5 offset:33280
	ds_read_b32 v206, v9 offset:32256
	ds_read_b128 v[208:211], v5 offset:33792
	v_add_f32_dpp v146, v146, v146 quad_perm:[1,0,3,2] row_mask:0xf bank_mask:0xf bound_ctrl:1
	v_pk_mul_f32 v[224:225], v[138:139], v[224:225]
	v_pk_fma_f32 v[224:225], v[140:141], v[226:227], v[224:225]
	v_add_f32_dpp v146, v146, v146 quad_perm:[2,3,0,1] row_mask:0xf bank_mask:0xf bound_ctrl:1
	v_add_f32 v150, v224, v225
	s_waitcnt lgkmcnt(12)
	v_add_f32_dpp v146, v146, v146 row_half_mirror row_mask:0xf bank_mask:0xf bound_ctrl:1
	v_pk_mul_f32 v[242:243], v[242:243], v[250:251] op_sel_hi:[1,0]
	v_pk_mul_f32 v[244:245], v[244:245], v[250:251] op_sel_hi:[1,0]
	v_add_f32_dpp v146, v146, v146 row_mirror row_mask:0xf bank_mask:0xf bound_ctrl:1
	v_pk_fma_f32 v[242:243], v[146:147], v[234:235], v[242:243] op_sel_hi:[0,1,1] neg_lo:[1,0,0] neg_hi:[1,0,0]
	v_pk_fma_f32 v[244:245], v[146:147], v[236:237], v[244:245] op_sel_hi:[0,1,1] neg_lo:[1,0,0] neg_hi:[1,0,0]
	v_pk_fma_f32 v[138:139], v[138:139], v[238:239], v[242:243]
	v_pk_fma_f32 v[140:141], v[140:141], v[240:241], v[244:245]
	v_pk_mul_f32 v[144:145], v[138:139], v[164:165]
	v_pk_fma_f32 v[144:145], v[140:141], v[166:167], v[144:145]
	v_add_f32 v146, v144, v145
	ds_read_b128 v[212:215], v5 offset:34048
	ds_read_b128 v[216:219], v5 offset:34304
	ds_read_b128 v[220:223], v5 offset:34560
	ds_read_b128 v[224:227], v5 offset:34816
	ds_read_b32 v228, v9 offset:33792
	ds_read_b128 v[230:233], v5 offset:35328
	v_add_f32_dpp v146, v146, v146 quad_perm:[1,0,3,2] row_mask:0xf bank_mask:0xf bound_ctrl:1
	v_pk_mul_f32 v[246:247], v[138:139], v[246:247]
	v_pk_fma_f32 v[246:247], v[140:141], v[248:249], v[246:247]
	v_add_f32_dpp v146, v146, v146 quad_perm:[2,3,0,1] row_mask:0xf bank_mask:0xf bound_ctrl:1
	v_add_f32 v151, v246, v247
	s_waitcnt lgkmcnt(12)
	v_add_f32_dpp v146, v146, v146 row_half_mirror row_mask:0xf bank_mask:0xf bound_ctrl:1
	v_pk_mul_f32 v[176:177], v[176:177], v[184:185] op_sel_hi:[1,0]
	v_pk_mul_f32 v[178:179], v[178:179], v[184:185] op_sel_hi:[1,0]
	v_add_f32_dpp v146, v146, v146 row_mirror row_mask:0xf bank_mask:0xf bound_ctrl:1
	v_pk_fma_f32 v[176:177], v[146:147], v[168:169], v[176:177] op_sel_hi:[0,1,1] neg_lo:[1,0,0] neg_hi:[1,0,0]
	v_pk_fma_f32 v[178:179], v[146:147], v[170:171], v[178:179] op_sel_hi:[0,1,1] neg_lo:[1,0,0] neg_hi:[1,0,0]
	v_pk_fma_f32 v[138:139], v[138:139], v[172:173], v[176:177]
	v_pk_fma_f32 v[140:141], v[140:141], v[174:175], v[178:179]
	v_pk_mul_f32 v[144:145], v[138:139], v[186:187]
	v_pk_fma_f32 v[144:145], v[140:141], v[188:189], v[144:145]
	v_add_f32 v146, v144, v145
	ds_read_b128 v[234:237], v5 offset:35584
	ds_read_b128 v[238:241], v5 offset:35840
	ds_read_b128 v[242:245], v5 offset:36096
	ds_read_b128 v[246:249], v5 offset:36352
	ds_read_b32 v250, v9 offset:35328
	ds_read_b128 v[164:167], v5 offset:36864
	v_add_f32_dpp v146, v146, v146 quad_perm:[1,0,3,2] row_mask:0xf bank_mask:0xf bound_ctrl:1
	v_pk_mul_f32 v[180:181], v[138:139], v[180:181]
	v_pk_fma_f32 v[180:181], v[140:141], v[182:183], v[180:181]
	v_add_f32_dpp v146, v146, v146 quad_perm:[2,3,0,1] row_mask:0xf bank_mask:0xf bound_ctrl:1
	v_add_f32 v152, v180, v181
	s_waitcnt lgkmcnt(12)
	v_add_f32_dpp v146, v146, v146 row_half_mirror row_mask:0xf bank_mask:0xf bound_ctrl:1
	v_pk_mul_f32 v[198:199], v[198:199], v[206:207] op_sel_hi:[1,0]
	v_pk_mul_f32 v[200:201], v[200:201], v[206:207] op_sel_hi:[1,0]
	v_add_f32_dpp v146, v146, v146 row_mirror row_mask:0xf bank_mask:0xf bound_ctrl:1
	v_pk_fma_f32 v[198:199], v[146:147], v[190:191], v[198:199] op_sel_hi:[0,1,1] neg_lo:[1,0,0] neg_hi:[1,0,0]
	v_pk_fma_f32 v[200:201], v[146:147], v[192:193], v[200:201] op_sel_hi:[0,1,1] neg_lo:[1,0,0] neg_hi:[1,0,0]
	v_pk_fma_f32 v[138:139], v[138:139], v[194:195], v[198:199]
	v_pk_fma_f32 v[140:141], v[140:141], v[196:197], v[200:201]
	v_pk_mul_f32 v[144:145], v[138:139], v[208:209]
	v_pk_fma_f32 v[144:145], v[140:141], v[210:211], v[144:145]
	v_add_f32 v146, v144, v145
	ds_read_b128 v[168:171], v5 offset:37120
	ds_read_b128 v[172:175], v5 offset:37376
	ds_read_b128 v[176:179], v5 offset:37632
	ds_read_b128 v[180:183], v5 offset:37888
	ds_read_b32 v184, v9 offset:36864
	ds_read_b128 v[186:189], v5 offset:38400
	v_add_f32_dpp v146, v146, v146 quad_perm:[1,0,3,2] row_mask:0xf bank_mask:0xf bound_ctrl:1
	v_pk_mul_f32 v[202:203], v[138:139], v[202:203]
	v_pk_fma_f32 v[202:203], v[140:141], v[204:205], v[202:203]
	v_add_f32_dpp v146, v146, v146 quad_perm:[2,3,0,1] row_mask:0xf bank_mask:0xf bound_ctrl:1
	v_add_f32 v153, v202, v203
	s_waitcnt lgkmcnt(12)
	v_add_f32_dpp v146, v146, v146 row_half_mirror row_mask:0xf bank_mask:0xf bound_ctrl:1
	v_pk_mul_f32 v[220:221], v[220:221], v[228:229] op_sel_hi:[1,0]
	v_pk_mul_f32 v[222:223], v[222:223], v[228:229] op_sel_hi:[1,0]
	v_add_f32_dpp v146, v146, v146 row_mirror row_mask:0xf bank_mask:0xf bound_ctrl:1
	v_pk_fma_f32 v[220:221], v[146:147], v[212:213], v[220:221] op_sel_hi:[0,1,1] neg_lo:[1,0,0] neg_hi:[1,0,0]
	v_pk_fma_f32 v[222:223], v[146:147], v[214:215], v[222:223] op_sel_hi:[0,1,1] neg_lo:[1,0,0] neg_hi:[1,0,0]
	v_pk_fma_f32 v[138:139], v[138:139], v[216:217], v[220:221]
	v_pk_fma_f32 v[140:141], v[140:141], v[218:219], v[222:223]
	v_pk_mul_f32 v[144:145], v[138:139], v[230:231]
	v_pk_fma_f32 v[144:145], v[140:141], v[232:233], v[144:145]
	v_add_f32 v146, v144, v145
	ds_read_b128 v[190:193], v5 offset:38656
	ds_read_b128 v[194:197], v5 offset:38912
	ds_read_b128 v[198:201], v5 offset:39168
	ds_read_b128 v[202:205], v5 offset:39424
	ds_read_b32 v206, v9 offset:38400
	ds_read_b128 v[208:211], v5 offset:39936
	v_add_f32_dpp v146, v146, v146 quad_perm:[1,0,3,2] row_mask:0xf bank_mask:0xf bound_ctrl:1
	v_pk_mul_f32 v[224:225], v[138:139], v[224:225]
	v_pk_fma_f32 v[224:225], v[140:141], v[226:227], v[224:225]
	v_add_f32_dpp v146, v146, v146 quad_perm:[2,3,0,1] row_mask:0xf bank_mask:0xf bound_ctrl:1
	v_add_f32 v154, v224, v225
	s_waitcnt lgkmcnt(12)
	v_add_f32_dpp v146, v146, v146 row_half_mirror row_mask:0xf bank_mask:0xf bound_ctrl:1
	v_pk_mul_f32 v[242:243], v[242:243], v[250:251] op_sel_hi:[1,0]
	v_pk_mul_f32 v[244:245], v[244:245], v[250:251] op_sel_hi:[1,0]
	v_add_f32_dpp v146, v146, v146 row_mirror row_mask:0xf bank_mask:0xf bound_ctrl:1
	v_pk_fma_f32 v[242:243], v[146:147], v[234:235], v[242:243] op_sel_hi:[0,1,1] neg_lo:[1,0,0] neg_hi:[1,0,0]
	v_pk_fma_f32 v[244:245], v[146:147], v[236:237], v[244:245] op_sel_hi:[0,1,1] neg_lo:[1,0,0] neg_hi:[1,0,0]
	v_pk_fma_f32 v[138:139], v[138:139], v[238:239], v[242:243]
	v_pk_fma_f32 v[140:141], v[140:141], v[240:241], v[244:245]
	v_pk_mul_f32 v[144:145], v[138:139], v[164:165]
	v_pk_fma_f32 v[144:145], v[140:141], v[166:167], v[144:145]
	v_add_f32 v146, v144, v145
	ds_read_b128 v[212:215], v5 offset:40192
	ds_read_b128 v[216:219], v5 offset:40448
	ds_read_b128 v[220:223], v5 offset:40704
	ds_read_b128 v[224:227], v5 offset:40960
	ds_read_b32 v228, v9 offset:39936
	ds_read_b128 v[230:233], v5 offset:41472
	v_add_f32_dpp v146, v146, v146 quad_perm:[1,0,3,2] row_mask:0xf bank_mask:0xf bound_ctrl:1
	v_pk_mul_f32 v[246:247], v[138:139], v[246:247]
	v_pk_fma_f32 v[246:247], v[140:141], v[248:249], v[246:247]
	v_add_f32_dpp v146, v146, v146 quad_perm:[2,3,0,1] row_mask:0xf bank_mask:0xf bound_ctrl:1
	v_add_f32 v155, v246, v247
	s_waitcnt lgkmcnt(12)
	v_add_f32_dpp v146, v146, v146 row_half_mirror row_mask:0xf bank_mask:0xf bound_ctrl:1
	v_pk_mul_f32 v[176:177], v[176:177], v[184:185] op_sel_hi:[1,0]
	v_pk_mul_f32 v[178:179], v[178:179], v[184:185] op_sel_hi:[1,0]
	v_add_f32_dpp v146, v146, v146 row_mirror row_mask:0xf bank_mask:0xf bound_ctrl:1
	v_pk_fma_f32 v[176:177], v[146:147], v[168:169], v[176:177] op_sel_hi:[0,1,1] neg_lo:[1,0,0] neg_hi:[1,0,0]
	v_pk_fma_f32 v[178:179], v[146:147], v[170:171], v[178:179] op_sel_hi:[0,1,1] neg_lo:[1,0,0] neg_hi:[1,0,0]
	v_pk_fma_f32 v[138:139], v[138:139], v[172:173], v[176:177]
	v_pk_fma_f32 v[140:141], v[140:141], v[174:175], v[178:179]
	v_pk_mul_f32 v[144:145], v[138:139], v[186:187]
	v_pk_fma_f32 v[144:145], v[140:141], v[188:189], v[144:145]
	v_add_f32 v146, v144, v145
	ds_read_b128 v[234:237], v5 offset:41728
	ds_read_b128 v[238:241], v5 offset:41984
	ds_read_b128 v[242:245], v5 offset:42240
	ds_read_b128 v[246:249], v5 offset:42496
	ds_read_b32 v250, v9 offset:41472
	ds_read_b128 v[164:167], v5 offset:43008
	v_add_f32_dpp v146, v146, v146 quad_perm:[1,0,3,2] row_mask:0xf bank_mask:0xf bound_ctrl:1
	v_pk_mul_f32 v[180:181], v[138:139], v[180:181]
	v_pk_fma_f32 v[180:181], v[140:141], v[182:183], v[180:181]
	v_add_f32_dpp v146, v146, v146 quad_perm:[2,3,0,1] row_mask:0xf bank_mask:0xf bound_ctrl:1
	v_add_f32 v156, v180, v181
	s_waitcnt lgkmcnt(12)
	v_add_f32_dpp v146, v146, v146 row_half_mirror row_mask:0xf bank_mask:0xf bound_ctrl:1
	v_pk_mul_f32 v[198:199], v[198:199], v[206:207] op_sel_hi:[1,0]
	v_pk_mul_f32 v[200:201], v[200:201], v[206:207] op_sel_hi:[1,0]
	v_add_f32_dpp v146, v146, v146 row_mirror row_mask:0xf bank_mask:0xf bound_ctrl:1
	v_pk_fma_f32 v[198:199], v[146:147], v[190:191], v[198:199] op_sel_hi:[0,1,1] neg_lo:[1,0,0] neg_hi:[1,0,0]
	v_pk_fma_f32 v[200:201], v[146:147], v[192:193], v[200:201] op_sel_hi:[0,1,1] neg_lo:[1,0,0] neg_hi:[1,0,0]
	v_pk_fma_f32 v[138:139], v[138:139], v[194:195], v[198:199]
	v_pk_fma_f32 v[140:141], v[140:141], v[196:197], v[200:201]
	v_pk_mul_f32 v[144:145], v[138:139], v[208:209]
	v_pk_fma_f32 v[144:145], v[140:141], v[210:211], v[144:145]
	v_add_f32 v146, v144, v145
	ds_read_b128 v[168:171], v5 offset:43264
	ds_read_b128 v[172:175], v5 offset:43520
	ds_read_b128 v[176:179], v5 offset:43776
	ds_read_b128 v[180:183], v5 offset:44032
	ds_read_b32 v184, v9 offset:43008
	ds_read_b128 v[186:189], v5 offset:44544
	v_add_f32_dpp v146, v146, v146 quad_perm:[1,0,3,2] row_mask:0xf bank_mask:0xf bound_ctrl:1
	v_pk_mul_f32 v[202:203], v[138:139], v[202:203]
	v_pk_fma_f32 v[202:203], v[140:141], v[204:205], v[202:203]
	v_add_f32_dpp v146, v146, v146 quad_perm:[2,3,0,1] row_mask:0xf bank_mask:0xf bound_ctrl:1
	v_add_f32 v157, v202, v203
	s_waitcnt lgkmcnt(12)
	v_add_f32_dpp v146, v146, v146 row_half_mirror row_mask:0xf bank_mask:0xf bound_ctrl:1
	v_pk_mul_f32 v[220:221], v[220:221], v[228:229] op_sel_hi:[1,0]
	v_pk_mul_f32 v[222:223], v[222:223], v[228:229] op_sel_hi:[1,0]
	v_add_f32_dpp v146, v146, v146 row_mirror row_mask:0xf bank_mask:0xf bound_ctrl:1
	v_pk_fma_f32 v[220:221], v[146:147], v[212:213], v[220:221] op_sel_hi:[0,1,1] neg_lo:[1,0,0] neg_hi:[1,0,0]
	v_pk_fma_f32 v[222:223], v[146:147], v[214:215], v[222:223] op_sel_hi:[0,1,1] neg_lo:[1,0,0] neg_hi:[1,0,0]
	v_pk_fma_f32 v[138:139], v[138:139], v[216:217], v[220:221]
	v_pk_fma_f32 v[140:141], v[140:141], v[218:219], v[222:223]
	v_pk_mul_f32 v[144:145], v[138:139], v[230:231]
	v_pk_fma_f32 v[144:145], v[140:141], v[232:233], v[144:145]
	v_add_f32 v146, v144, v145
	ds_read_b128 v[190:193], v5 offset:44800
	ds_read_b128 v[194:197], v5 offset:45056
	ds_read_b128 v[198:201], v5 offset:45312
	ds_read_b128 v[202:205], v5 offset:45568
	ds_read_b32 v206, v9 offset:44544
	ds_read_b128 v[208:211], v5 offset:46080
	v_add_f32_dpp v146, v146, v146 quad_perm:[1,0,3,2] row_mask:0xf bank_mask:0xf bound_ctrl:1
	v_pk_mul_f32 v[224:225], v[138:139], v[224:225]
	v_pk_fma_f32 v[224:225], v[140:141], v[226:227], v[224:225]
	v_add_f32_dpp v146, v146, v146 quad_perm:[2,3,0,1] row_mask:0xf bank_mask:0xf bound_ctrl:1
	v_add_f32 v158, v224, v225
	s_waitcnt lgkmcnt(12)
	v_add_f32_dpp v146, v146, v146 row_half_mirror row_mask:0xf bank_mask:0xf bound_ctrl:1
	v_pk_mul_f32 v[242:243], v[242:243], v[250:251] op_sel_hi:[1,0]
	v_pk_mul_f32 v[244:245], v[244:245], v[250:251] op_sel_hi:[1,0]
	v_add_f32_dpp v146, v146, v146 row_mirror row_mask:0xf bank_mask:0xf bound_ctrl:1
	v_pk_fma_f32 v[242:243], v[146:147], v[234:235], v[242:243] op_sel_hi:[0,1,1] neg_lo:[1,0,0] neg_hi:[1,0,0]
	v_pk_fma_f32 v[244:245], v[146:147], v[236:237], v[244:245] op_sel_hi:[0,1,1] neg_lo:[1,0,0] neg_hi:[1,0,0]
	v_pk_fma_f32 v[138:139], v[138:139], v[238:239], v[242:243]
	v_pk_fma_f32 v[140:141], v[140:141], v[240:241], v[244:245]
	v_pk_mul_f32 v[144:145], v[138:139], v[164:165]
	v_pk_fma_f32 v[144:145], v[140:141], v[166:167], v[144:145]
	v_add_f32 v146, v144, v145
	ds_read_b128 v[212:215], v5 offset:46336
	ds_read_b128 v[216:219], v5 offset:46592
	ds_read_b128 v[220:223], v5 offset:46848
	ds_read_b128 v[224:227], v5 offset:47104
	ds_read_b32 v228, v9 offset:46080
	ds_read_b128 v[230:233], v5 offset:47616
	v_add_f32_dpp v146, v146, v146 quad_perm:[1,0,3,2] row_mask:0xf bank_mask:0xf bound_ctrl:1
	v_pk_mul_f32 v[246:247], v[138:139], v[246:247]
	v_pk_fma_f32 v[246:247], v[140:141], v[248:249], v[246:247]
	v_add_f32_dpp v146, v146, v146 quad_perm:[2,3,0,1] row_mask:0xf bank_mask:0xf bound_ctrl:1
	v_add_f32 v159, v246, v247
	s_waitcnt lgkmcnt(12)
	v_add_f32_dpp v146, v146, v146 row_half_mirror row_mask:0xf bank_mask:0xf bound_ctrl:1
	v_pk_mul_f32 v[176:177], v[176:177], v[184:185] op_sel_hi:[1,0]
	v_pk_mul_f32 v[178:179], v[178:179], v[184:185] op_sel_hi:[1,0]
	v_add_f32_dpp v146, v146, v146 row_mirror row_mask:0xf bank_mask:0xf bound_ctrl:1
	v_pk_fma_f32 v[176:177], v[146:147], v[168:169], v[176:177] op_sel_hi:[0,1,1] neg_lo:[1,0,0] neg_hi:[1,0,0]
	v_pk_fma_f32 v[178:179], v[146:147], v[170:171], v[178:179] op_sel_hi:[0,1,1] neg_lo:[1,0,0] neg_hi:[1,0,0]
	v_pk_fma_f32 v[138:139], v[138:139], v[172:173], v[176:177]
	v_pk_fma_f32 v[140:141], v[140:141], v[174:175], v[178:179]
	v_pk_mul_f32 v[144:145], v[138:139], v[186:187]
	v_pk_fma_f32 v[144:145], v[140:141], v[188:189], v[144:145]
	v_add_f32 v146, v144, v145
	ds_read_b128 v[234:237], v5 offset:47872
	ds_read_b128 v[238:241], v5 offset:48128
	ds_read_b128 v[242:245], v5 offset:48384
	ds_read_b128 v[246:249], v5 offset:48640
	ds_read_b32 v250, v9 offset:47616
	v_add_f32_dpp v146, v146, v146 quad_perm:[1,0,3,2] row_mask:0xf bank_mask:0xf bound_ctrl:1
	v_pk_mul_f32 v[180:181], v[138:139], v[180:181]
	v_pk_fma_f32 v[180:181], v[140:141], v[182:183], v[180:181]
	v_add_f32_dpp v146, v146, v146 quad_perm:[2,3,0,1] row_mask:0xf bank_mask:0xf bound_ctrl:1
	v_add_f32 v160, v180, v181
	s_waitcnt lgkmcnt(11)
	v_add_f32_dpp v146, v146, v146 row_half_mirror row_mask:0xf bank_mask:0xf bound_ctrl:1
	v_pk_mul_f32 v[198:199], v[198:199], v[206:207] op_sel_hi:[1,0]
	v_pk_mul_f32 v[200:201], v[200:201], v[206:207] op_sel_hi:[1,0]
	v_add_f32_dpp v146, v146, v146 row_mirror row_mask:0xf bank_mask:0xf bound_ctrl:1
	v_pk_fma_f32 v[198:199], v[146:147], v[190:191], v[198:199] op_sel_hi:[0,1,1] neg_lo:[1,0,0] neg_hi:[1,0,0]
	v_pk_fma_f32 v[200:201], v[146:147], v[192:193], v[200:201] op_sel_hi:[0,1,1] neg_lo:[1,0,0] neg_hi:[1,0,0]
	v_pk_fma_f32 v[138:139], v[138:139], v[194:195], v[198:199]
	v_pk_fma_f32 v[140:141], v[140:141], v[196:197], v[200:201]
	v_pk_mul_f32 v[144:145], v[138:139], v[208:209]
	v_pk_fma_f32 v[144:145], v[140:141], v[210:211], v[144:145]
	v_add_f32 v146, v144, v145
	s_nop 1
	v_add_f32_dpp v146, v146, v146 quad_perm:[1,0,3,2] row_mask:0xf bank_mask:0xf bound_ctrl:1
	v_pk_mul_f32 v[202:203], v[138:139], v[202:203]
	v_pk_fma_f32 v[202:203], v[140:141], v[204:205], v[202:203]
	v_add_f32_dpp v146, v146, v146 quad_perm:[2,3,0,1] row_mask:0xf bank_mask:0xf bound_ctrl:1
	v_add_f32 v161, v202, v203
	s_waitcnt lgkmcnt(5)
	v_add_f32_dpp v146, v146, v146 row_half_mirror row_mask:0xf bank_mask:0xf bound_ctrl:1
	v_pk_mul_f32 v[220:221], v[220:221], v[228:229] op_sel_hi:[1,0]
	v_pk_mul_f32 v[222:223], v[222:223], v[228:229] op_sel_hi:[1,0]
	v_add_f32_dpp v146, v146, v146 row_mirror row_mask:0xf bank_mask:0xf bound_ctrl:1
	v_pk_fma_f32 v[220:221], v[146:147], v[212:213], v[220:221] op_sel_hi:[0,1,1] neg_lo:[1,0,0] neg_hi:[1,0,0]
	v_pk_fma_f32 v[222:223], v[146:147], v[214:215], v[222:223] op_sel_hi:[0,1,1] neg_lo:[1,0,0] neg_hi:[1,0,0]
	v_pk_fma_f32 v[138:139], v[138:139], v[216:217], v[220:221]
	v_pk_fma_f32 v[140:141], v[140:141], v[218:219], v[222:223]
	v_pk_mul_f32 v[144:145], v[138:139], v[230:231]
	v_pk_fma_f32 v[144:145], v[140:141], v[232:233], v[144:145]
	v_add_f32 v146, v144, v145
	s_nop 1
	v_add_f32_dpp v146, v146, v146 quad_perm:[1,0,3,2] row_mask:0xf bank_mask:0xf bound_ctrl:1
	v_pk_mul_f32 v[224:225], v[138:139], v[224:225]
	v_pk_fma_f32 v[224:225], v[140:141], v[226:227], v[224:225]
	v_add_f32_dpp v146, v146, v146 quad_perm:[2,3,0,1] row_mask:0xf bank_mask:0xf bound_ctrl:1
	v_add_f32 v162, v224, v225
	s_waitcnt lgkmcnt(0)
	v_add_f32_dpp v146, v146, v146 row_half_mirror row_mask:0xf bank_mask:0xf bound_ctrl:1
	v_pk_mul_f32 v[242:243], v[242:243], v[250:251] op_sel_hi:[1,0]
	v_pk_mul_f32 v[244:245], v[244:245], v[250:251] op_sel_hi:[1,0]
	v_add_f32_dpp v146, v146, v146 row_mirror row_mask:0xf bank_mask:0xf bound_ctrl:1
	v_pk_fma_f32 v[242:243], v[146:147], v[234:235], v[242:243] op_sel_hi:[0,1,1] neg_lo:[1,0,0] neg_hi:[1,0,0]
	v_pk_fma_f32 v[244:245], v[146:147], v[236:237], v[244:245] op_sel_hi:[0,1,1] neg_lo:[1,0,0] neg_hi:[1,0,0]
	v_pk_fma_f32 v[138:139], v[138:139], v[238:239], v[242:243]
	v_pk_fma_f32 v[140:141], v[140:141], v[240:241], v[244:245]
	v_pk_mul_f32 v[246:247], v[138:139], v[246:247]
	v_pk_fma_f32 v[246:247], v[140:141], v[248:249], v[246:247]
	v_add_f32 v163, v246, v247
	s_nop 0
	v_add_f32_dpp v102, v148, v148 row_mirror row_mask:0xf bank_mask:0x3 bound_ctrl:1
	v_add_f32_dpp v102, v156, v156 row_mirror row_mask:0xf bank_mask:0xc bound_ctrl:1
	v_add_f32_dpp v103, v149, v149 row_mirror row_mask:0xf bank_mask:0x3 bound_ctrl:1
	v_add_f32_dpp v103, v157, v157 row_mirror row_mask:0xf bank_mask:0xc bound_ctrl:1
	v_add_f32_dpp v104, v150, v150 row_mirror row_mask:0xf bank_mask:0x3 bound_ctrl:1
	v_add_f32_dpp v104, v158, v158 row_mirror row_mask:0xf bank_mask:0xc bound_ctrl:1
	v_add_f32_dpp v105, v151, v151 row_mirror row_mask:0xf bank_mask:0x3 bound_ctrl:1
	v_add_f32_dpp v105, v159, v159 row_mirror row_mask:0xf bank_mask:0xc bound_ctrl:1
	v_add_f32_dpp v106, v152, v152 row_mirror row_mask:0xf bank_mask:0x3 bound_ctrl:1
	v_add_f32_dpp v106, v160, v160 row_mirror row_mask:0xf bank_mask:0xc bound_ctrl:1
	v_add_f32_dpp v107, v153, v153 row_mirror row_mask:0xf bank_mask:0x3 bound_ctrl:1
	v_add_f32_dpp v107, v161, v161 row_mirror row_mask:0xf bank_mask:0xc bound_ctrl:1
	v_add_f32_dpp v108, v154, v154 row_mirror row_mask:0xf bank_mask:0x3 bound_ctrl:1
	v_add_f32_dpp v108, v162, v162 row_mirror row_mask:0xf bank_mask:0xc bound_ctrl:1
	v_add_f32_dpp v109, v155, v155 row_mirror row_mask:0xf bank_mask:0x3 bound_ctrl:1
	v_add_f32_dpp v109, v163, v163 row_mirror row_mask:0xf bank_mask:0xc bound_ctrl:1
	v_add_f32_dpp v110, v102, v102 row_half_mirror row_mask:0xf bank_mask:0x5 bound_ctrl:1
	v_add_f32_dpp v110, v106, v106 row_half_mirror row_mask:0xf bank_mask:0xa bound_ctrl:1
	v_add_f32_dpp v111, v103, v103 row_half_mirror row_mask:0xf bank_mask:0x5 bound_ctrl:1
	v_add_f32_dpp v111, v107, v107 row_half_mirror row_mask:0xf bank_mask:0xa bound_ctrl:1
	v_add_f32_dpp v112, v104, v104 row_half_mirror row_mask:0xf bank_mask:0x5 bound_ctrl:1
	v_add_f32_dpp v112, v108, v108 row_half_mirror row_mask:0xf bank_mask:0xa bound_ctrl:1
	v_add_f32_dpp v113, v105, v105 row_half_mirror row_mask:0xf bank_mask:0x5 bound_ctrl:1
	v_add_f32_dpp v113, v109, v109 row_half_mirror row_mask:0xf bank_mask:0xa bound_ctrl:1
	s_mov_b32 vcc_lo, 0xcccccccc
	s_mov_b32 vcc_hi, 0xcccccccc
	v_cndmask_b32 v116, v112, v110, vcc
	v_cndmask_b32 v117, v113, v111, vcc
	v_cndmask_b32 v114, v110, v112, vcc
	v_cndmask_b32 v115, v111, v113, vcc
	v_add_f32_dpp v114, v116, v114 quad_perm:[2,3,0,1] row_mask:0xf bank_mask:0xf bound_ctrl:1
	v_add_f32_dpp v115, v117, v115 quad_perm:[2,3,0,1] row_mask:0xf bank_mask:0xf bound_ctrl:1
	s_mov_b32 vcc_lo, 0xaaaaaaaa
	s_mov_b32 vcc_hi, 0xaaaaaaaa
	v_cndmask_b32 v116, v115, v114, vcc
	v_cndmask_b32 v117, v114, v115, vcc
	s_nop 0
	v_add_f32_dpp v19, v116, v117 quad_perm:[1,0,3,2] row_mask:0xf bank_mask:0xf bound_ctrl:1

; __device__ __forceinline__ void scan_unit(const Ctx& C0, const float* scn, int T, int quarter, const float* S0, float* Sout, unsigned char* obase, int mode) {
;     ...
;             if (mode == 0) { *(float*)(obase + (size_t)(k * 32 + q) * UPITCH_B + rl * 4) = osel0; *(float*)(obase + (size_t)(k * 32 + 16 + q) * UPITCH_B + rl * 4) = osel1; }
	v_lshl_add_u64 v[14:15], v[6:7], 0, s[0:1]
	v_add_co_u32_e32 v16, vcc, 0xfc29000, v14
	s_mov_b32 s8, 0xfc7f000
	s_nop 0
	v_addc_co_u32_e32 v17, vcc, 0, v15, vcc
	global_store_dword v[16:17], v18, off offset:768
	v_add_co_u32_e32 v16, vcc, 0xfc54000, v14
	s_add_u32 s0, s0, 0xac000
	s_nop 0
	v_addc_co_u32_e32 v17, vcc, 0, v15, vcc
	global_store_dword v[16:17], v19, off offset:768
	s_barrier
	ds_read_b128 v[164:167], v10 offset:0
	ds_read_b128 v[168:171], v10 offset:256
	ds_read_b128 v[172:175], v10 offset:512
	ds_read_b128 v[176:179], v10 offset:768
	ds_read_b128 v[180:183], v10 offset:1024
	ds_read_b32 v184, v11 offset:0
	ds_read_b128 v[186:189], v10 offset:1536
	ds_read_b128 v[190:193], v10 offset:1792
	ds_read_b128 v[194:197], v10 offset:2048
	ds_read_b128 v[198:201], v10 offset:2304
	ds_read_b128 v[202:205], v10 offset:2560
	ds_read_b32 v206, v11 offset:1536
	ds_read_b128 v[208:211], v10 offset:3072
	s_waitcnt lgkmcnt(12)
	v_pk_mul_f32 v[144:145], v[138:139], v[164:165]
	v_pk_fma_f32 v[144:145], v[140:141], v[166:167], v[144:145]
	v_add_f32 v146, v144, v145
	ds_read_b128 v[212:215], v10 offset:3328
	ds_read_b128 v[216:219], v10 offset:3584
	ds_read_b128 v[220:223], v10 offset:3840
	ds_read_b128 v[224:227], v10 offset:4096
	ds_read_b32 v228, v11 offset:3072
	ds_read_b128 v[230:233], v10 offset:4608
	v_add_f32_dpp v146, v146, v146 quad_perm:[1,0,3,2] row_mask:0xf bank_mask:0xf bound_ctrl:1
	s_nop 0
	s_nop 0
	v_add_f32_dpp v146, v146, v146 quad_perm:[2,3,0,1] row_mask:0xf bank_mask:0xf bound_ctrl:1
	s_nop 0
	s_waitcnt lgkmcnt(12)
	v_add_f32_dpp v146, v146, v146 row_half_mirror row_mask:0xf bank_mask:0xf bound_ctrl:1
	v_pk_mul_f32 v[176:177], v[176:177], v[184:185] op_sel_hi:[1,0]
	v_pk_mul_f32 v[178:179], v[178:179], v[184:185] op_sel_hi:[1,0]
	v_add_f32_dpp v146, v146, v146 row_mirror row_mask:0xf bank_mask:0xf bound_ctrl:1
	v_pk_fma_f32 v[176:177], v[146:147], v[168:169], v[176:177] op_sel_hi:[0,1,1] neg_lo:[1,0,0] neg_hi:[1,0,0]
	v_pk_fma_f32 v[178:179], v[146:147], v[170:171], v[178:179] op_sel_hi:[0,1,1] neg_lo:[1,0,0] neg_hi:[1,0,0]
	v_pk_fma_f32 v[138:139], v[138:139], v[172:173], v[176:177]
	v_pk_fma_f32 v[140:141], v[140:141], v[174:175], v[178:179]
	v_pk_mul_f32 v[144:145], v[138:139], v[186:187]
	v_pk_fma_f32 v[144:145], v[140:141], v[188:189], v[144:145]
	v_add_f32 v146, v144, v145
	ds_read_b128 v[234:237], v10 offset:4864
	ds_read_b128 v[238:241], v10 offset:5120
	ds_read_b128 v[242:245], v10 offset:5376
	ds_read_b128 v[246:249], v10 offset:5632
	ds_read_b32 v250, v11 offset:4608
	ds_read_b128 v[164:167], v10 offset:6144
	v_add_f32_dpp v146, v146, v146 quad_perm:[1,0,3,2] row_mask:0xf bank_mask:0xf bound_ctrl:1
	v_pk_mul_f32 v[180:181], v[138:139], v[180:181]
	v_pk_fma_f32 v[180:181], v[140:141], v[182:183], v[180:181]
	v_add_f32_dpp v146, v146, v146 quad_perm:[2,3,0,1] row_mask:0xf bank_mask:0xf bound_ctrl:1
	v_add_f32 v148, v180, v181
	s_waitcnt lgkmcnt(12)
	v_add_f32_dpp v146, v146, v146 row_half_mirror row_mask:0xf bank_mask:0xf bound_ctrl:1
	v_pk_mul_f32 v[198:199], v[198:199], v[206:207] op_sel_hi:[1,0]
	v_pk_mul_f32 v[200:201], v[200:201], v[206:207] op_sel_hi:[1,0]
	v_add_f32_dpp v146, v146, v146 row_mirror row_mask:0xf bank_mask:0xf bound_ctrl:1
	v_pk_fma_f32 v[198:199], v[146:147], v[190:191], v[198:199] op_sel_hi:[0,1,1] neg_lo:[1,0,0] neg_hi:[1,0,0]
	v_pk_fma_f32 v[200:201], v[146:147], v[192:193], v[200:201] op_sel_hi:[0,1,1] neg_lo:[1,0,0] neg_hi:[1,0,0]
	v_pk_fma_f32 v[138:139], v[138:139], v[194:195], v[198:199]
	v_pk_fma_f32 v[140:141], v[140:141], v[196:197], v[200:201]
	v_pk_mul_f32 v[144:145], v[138:139], v[208:209]
	v_pk_fma_f32 v[144:145], v[140:141], v[210:211], v[144:145]
	v_add_f32 v146, v144, v145
	ds_read_b128 v[168:171], v10 offset:6400
	ds_read_b128 v[172:175], v10 offset:6656
	ds_read_b128 v[176:179], v10 offset:6912
	ds_read_b128 v[180:183], v10 offset:7168
	ds_read_b32 v184, v11 offset:6144
	ds_read_b128 v[186:189], v10 offset:7680
	v_add_f32_dpp v146, v146, v146 quad_perm:[1,0,3,2] row_mask:0xf bank_mask:0xf bound_ctrl:1
	v_pk_mul_f32 v[202:203], v[138:139], v[202:203]
	v_pk_fma_f32 v[202:203], v[140:141], v[204:205], v[202:203]
	v_add_f32_dpp v146, v146, v146 quad_perm:[2,3,0,1] row_mask:0xf bank_mask:0xf bound_ctrl:1
	v_add_f32 v149, v202, v203
	s_waitcnt lgkmcnt(12)
	v_add_f32_dpp v146, v146, v146 row_half_mirror row_mask:0xf bank_mask:0xf bound_ctrl:1
	v_pk_mul_f32 v[220:221], v[220:221], v[228:229] op_sel_hi:[1,0]
	v_pk_mul_f32 v[222:223], v[222:223], v[228:229] op_sel_hi:[1,0]
	v_add_f32_dpp v146, v146, v146 row_mirror row_mask:0xf bank_mask:0xf bound_ctrl:1
	v_pk_fma_f32 v[220:221], v[146:147], v[212:213], v[220:221] op_sel_hi:[0,1,1] neg_lo:[1,0,0] neg_hi:[1,0,0]
	v_pk_fma_f32 v[222:223], v[146:147], v[214:215], v[222:223] op_sel_hi:[0,1,1] neg_lo:[1,0,0] neg_hi:[1,0,0]
	v_pk_fma_f32 v[138:139], v[138:139], v[216:217], v[220:221]
	v_pk_fma_f32 v[140:141], v[140:141], v[218:219], v[222:223]
	v_pk_mul_f32 v[144:145], v[138:139], v[230:231]
	v_pk_fma_f32 v[144:145], v[140:141], v[232:233], v[144:145]
	v_add_f32 v146, v144, v145
	ds_read_b128 v[190:193], v10 offset:7936
	ds_read_b128 v[194:197], v10 offset:8192
	ds_read_b128 v[198:201], v10 offset:8448
	ds_read_b128 v[202:205], v10 offset:8704
	ds_read_b32 v206, v11 offset:7680
	ds_read_b128 v[208:211], v10 offset:9216
	v_add_f32_dpp v146, v146, v146 quad_perm:[1,0,3,2] row_mask:0xf bank_mask:0xf bound_ctrl:1
	v_pk_mul_f32 v[224:225], v[138:139], v[224:225]
	v_pk_fma_f32 v[224:225], v[140:141], v[226:227], v[224:225]
	v_add_f32_dpp v146, v146, v146 quad_perm:[2,3,0,1] row_mask:0xf bank_mask:0xf bound_ctrl:1
	v_add_f32 v150, v224, v225
	s_waitcnt lgkmcnt(12)
	v_add_f32_dpp v146, v146, v146 row_half_mirror row_mask:0xf bank_mask:0xf bound_ctrl:1
	v_pk_mul_f32 v[242:243], v[242:243], v[250:251] op_sel_hi:[1,0]
	v_pk_mul_f32 v[244:245], v[244:245], v[250:251] op_sel_hi:[1,0]
	v_add_f32_dpp v146, v146, v146 row_mirror row_mask:0xf bank_mask:0xf bound_ctrl:1
	v_pk_fma_f32 v[242:243], v[146:147], v[234:235], v[242:243] op_sel_hi:[0,1,1] neg_lo:[1,0,0] neg_hi:[1,0,0]
	v_pk_fma_f32 v[244:245], v[146:147], v[236:237], v[244:245] op_sel_hi:[0,1,1] neg_lo:[1,0,0] neg_hi:[1,0,0]
	v_pk_fma_f32 v[138:139], v[138:139], v[238:239], v[242:243]
	v_pk_fma_f32 v[140:141], v[140:141], v[240:241], v[244:245]
	v_pk_mul_f32 v[144:145], v[138:139], v[164:165]
	v_pk_fma_f32 v[144:145], v[140:141], v[166:167], v[144:145]
	v_add_f32 v146, v144, v145
	ds_read_b128 v[212:215], v10 offset:9472
	ds_read_b128 v[216:219], v10 offset:9728
	ds_read_b128 v[220:223], v10 offset:9984
	ds_read_b128 v[224:227], v10 offset:10240
	ds_read_b32 v228, v11 offset:9216
	ds_read_b128 v[230:233], v10 offset:10752
	v_add_f32_dpp v146, v146, v146 quad_perm:[1,0,3,2] row_mask:0xf bank_mask:0xf bound_ctrl:1
	v_pk_mul_f32 v[246:247], v[138:139], v[246:247]
	v_pk_fma_f32 v[246:247], v[140:141], v[248:249], v[246:247]
	v_add_f32_dpp v146, v146, v146 quad_perm:[2,3,0,1] row_mask:0xf bank_mask:0xf bound_ctrl:1
	v_add_f32 v151, v246, v247
	s_waitcnt lgkmcnt(12)
	v_add_f32_dpp v146, v146, v146 row_half_mirror row_mask:0xf bank_mask:0xf bound_ctrl:1
	v_pk_mul_f32 v[176:177], v[176:177], v[184:185] op_sel_hi:[1,0]
	v_pk_mul_f32 v[178:179], v[178:179], v[184:185] op_sel_hi:[1,0]
	v_add_f32_dpp v146, v146, v146 row_mirror row_mask:0xf bank_mask:0xf bound_ctrl:1
	v_pk_fma_f32 v[176:177], v[146:147], v[168:169], v[176:177] op_sel_hi:[0,1,1] neg_lo:[1,0,0] neg_hi:[1,0,0]
	v_pk_fma_f32 v[178:179], v[146:147], v[170:171], v[178:179] op_sel_hi:[0,1,1] neg_lo:[1,0,0] neg_hi:[1,0,0]
	v_pk_fma_f32 v[138:139], v[138:139], v[172:173], v[176:177]
	v_pk_fma_f32 v[140:141], v[140:141], v[174:175], v[178:179]
	v_pk_mul_f32 v[144:145], v[138:139], v[186:187]
	v_pk_fma_f32 v[144:145], v[140:141], v[188:189], v[144:145]
	v_add_f32 v146, v144, v145
	ds_read_b128 v[234:237], v10 offset:11008
	ds_read_b128 v[238:241], v10 offset:11264
	ds_read_b128 v[242:245], v10 offset:11520
	ds_read_b128 v[246:249], v10 offset:11776
	ds_read_b32 v250, v11 offset:10752
	ds_read_b128 v[164:167], v10 offset:12288
	v_add_f32_dpp v146, v146, v146 quad_perm:[1,0,3,2] row_mask:0xf bank_mask:0xf bound_ctrl:1
	v_pk_mul_f32 v[180:181], v[138:139], v[180:181]
	v_pk_fma_f32 v[180:181], v[140:141], v[182:183], v[180:181]
	v_add_f32_dpp v146, v146, v146 quad_perm:[2,3,0,1] row_mask:0xf bank_mask:0xf bound_ctrl:1
	v_add_f32 v152, v180, v181
	s_waitcnt lgkmcnt(12)
	v_add_f32_dpp v146, v146, v146 row_half_mirror row_mask:0xf bank_mask:0xf bound_ctrl:1
	v_pk_mul_f32 v[198:199], v[198:199], v[206:207] op_sel_hi:[1,0]
	v_pk_mul_f32 v[200:201], v[200:201], v[206:207] op_sel_hi:[1,0]
	v_add_f32_dpp v146, v146, v146 row_mirror row_mask:0xf bank_mask:0xf bound_ctrl:1
	v_pk_fma_f32 v[198:199], v[146:147], v[190:191], v[198:199] op_sel_hi:[0,1,1] neg_lo:[1,0,0] neg_hi:[1,0,0]
	v_pk_fma_f32 v[200:201], v[146:147], v[192:193], v[200:201] op_sel_hi:[0,1,1] neg_lo:[1,0,0] neg_hi:[1,0,0]
	v_pk_fma_f32 v[138:139], v[138:139], v[194:195], v[198:199]
	v_pk_fma_f32 v[140:141], v[140:141], v[196:197], v[200:201]
	v_pk_mul_f32 v[144:145], v[138:139], v[208:209]
	v_pk_fma_f32 v[144:145], v[140:141], v[210:211], v[144:145]
	v_add_f32 v146, v144, v145
	ds_read_b128 v[168:171], v10 offset:12544
	ds_read_b128 v[172:175], v10 offset:12800
	ds_read_b128 v[176:179], v10 offset:13056
	ds_read_b128 v[180:183], v10 offset:13312
	ds_read_b32 v184, v11 offset:12288
	ds_read_b128 v[186:189], v10 offset:13824
	v_add_f32_dpp v146, v146, v146 quad_perm:[1,0,3,2] row_mask:0xf bank_mask:0xf bound_ctrl:1
	v_pk_mul_f32 v[202:203], v[138:139], v[202:203]
	v_pk_fma_f32 v[202:203], v[140:141], v[204:205], v[202:203]
	v_add_f32_dpp v146, v146, v146 quad_perm:[2,3,0,1] row_mask:0xf bank_mask:0xf bound_ctrl:1
	v_add_f32 v153, v202, v203
	s_waitcnt lgkmcnt(12)
	v_add_f32_dpp v146, v146, v146 row_half_mirror row_mask:0xf bank_mask:0xf bound_ctrl:1
	v_pk_mul_f32 v[220:221], v[220:221], v[228:229] op_sel_hi:[1,0]
	v_pk_mul_f32 v[222:223], v[222:223], v[228:229] op_sel_hi:[1,0]
	v_add_f32_dpp v146, v146, v146 row_mirror row_mask:0xf bank_mask:0xf bound_ctrl:1
	v_pk_fma_f32 v[220:221], v[146:147], v[212:213], v[220:221] op_sel_hi:[0,1,1] neg_lo:[1,0,0] neg_hi:[1,0,0]
	v_pk_fma_f32 v[222:223], v[146:147], v[214:215], v[222:223] op_sel_hi:[0,1,1] neg_lo:[1,0,0] neg_hi:[1,0,0]
	v_pk_fma_f32 v[138:139], v[138:139], v[216:217], v[220:221]
	v_pk_fma_f32 v[140:141], v[140:141], v[218:219], v[222:223]
	v_pk_mul_f32 v[144:145], v[138:139], v[230:231]
	v_pk_fma_f32 v[144:145], v[140:141], v[232:233], v[144:145]
	v_add_f32 v146, v144, v145
	ds_read_b128 v[190:193], v10 offset:14080
	ds_read_b128 v[194:197], v10 offset:14336
	ds_read_b128 v[198:201], v10 offset:14592
	ds_read_b128 v[202:205], v10 offset:14848
	ds_read_b32 v206, v11 offset:13824
	ds_read_b128 v[208:211], v10 offset:15360
	v_add_f32_dpp v146, v146, v146 quad_perm:[1,0,3,2] row_mask:0xf bank_mask:0xf bound_ctrl:1
	v_pk_mul_f32 v[224:225], v[138:139], v[224:225]
	v_pk_fma_f32 v[224:225], v[140:141], v[226:227], v[224:225]
	v_add_f32_dpp v146, v146, v146 quad_perm:[2,3,0,1] row_mask:0xf bank_mask:0xf bound_ctrl:1
	v_add_f32 v154, v224, v225
	s_waitcnt lgkmcnt(12)
	v_add_f32_dpp v146, v146, v146 row_half_mirror row_mask:0xf bank_mask:0xf bound_ctrl:1
	v_pk_mul_f32 v[242:243], v[242:243], v[250:251] op_sel_hi:[1,0]
	v_pk_mul_f32 v[244:245], v[244:245], v[250:251] op_sel_hi:[1,0]
	v_add_f32_dpp v146, v146, v146 row_mirror row_mask:0xf bank_mask:0xf bound_ctrl:1
	v_pk_fma_f32 v[242:243], v[146:147], v[234:235], v[242:243] op_sel_hi:[0,1,1] neg_lo:[1,0,0] neg_hi:[1,0,0]
	v_pk_fma_f32 v[244:245], v[146:147], v[236:237], v[244:245] op_sel_hi:[0,1,1] neg_lo:[1,0,0] neg_hi:[1,0,0]
	v_pk_fma_f32 v[138:139], v[138:139], v[238:239], v[242:243]
	v_pk_fma_f32 v[140:141], v[140:141], v[240:241], v[244:245]
	v_pk_mul_f32 v[144:145], v[138:139], v[164:165]
	v_pk_fma_f32 v[144:145], v[140:141], v[166:167], v[144:145]
	v_add_f32 v146, v144, v145
	ds_read_b128 v[212:215], v10 offset:15616
	ds_read_b128 v[216:219], v10 offset:15872
	ds_read_b128 v[220:223], v10 offset:16128
	ds_read_b128 v[224:227], v10 offset:16384
	ds_read_b32 v228, v11 offset:15360
	ds_read_b128 v[230:233], v10 offset:16896
	v_add_f32_dpp v146, v146, v146 quad_perm:[1,0,3,2] row_mask:0xf bank_mask:0xf bound_ctrl:1
	v_pk_mul_f32 v[246:247], v[138:139], v[246:247]
	v_pk_fma_f32 v[246:247], v[140:141], v[248:249], v[246:247]
	v_add_f32_dpp v146, v146, v146 quad_perm:[2,3,0,1] row_mask:0xf bank_mask:0xf bound_ctrl:1
	v_add_f32 v155, v246, v247
	s_waitcnt lgkmcnt(12)
	v_add_f32_dpp v146, v146, v146 row_half_mirror row_mask:0xf bank_mask:0xf bound_ctrl:1
	v_pk_mul_f32 v[176:177], v[176:177], v[184:185] op_sel_hi:[1,0]
	v_pk_mul_f32 v[178:179], v[178:179], v[184:185] op_sel_hi:[1,0]
	v_add_f32_dpp v146, v146, v146 row_mirror row_mask:0xf bank_mask:0xf bound_ctrl:1
	v_pk_fma_f32 v[176:177], v[146:147], v[168:169], v[176:177] op_sel_hi:[0,1,1] neg_lo:[1,0,0] neg_hi:[1,0,0]
	v_pk_fma_f32 v[178:179], v[146:147], v[170:171], v[178:179] op_sel_hi:[0,1,1] neg_lo:[1,0,0] neg_hi:[1,0,0]
	v_pk_fma_f32 v[138:139], v[138:139], v[172:173], v[176:177]
	v_pk_fma_f32 v[140:141], v[140:141], v[174:175], v[178:179]
	v_pk_mul_f32 v[144:145], v[138:139], v[186:187]
	v_pk_fma_f32 v[144:145], v[140:141], v[188:189], v[144:145]
	v_add_f32 v146, v144, v145
	ds_read_b128 v[234:237], v10 offset:17152
	ds_read_b128 v[238:241], v10 offset:17408
	ds_read_b128 v[242:245], v10 offset:17664
	ds_read_b128 v[246:249], v10 offset:17920
	ds_read_b32 v250, v11 offset:16896
	ds_read_b128 v[164:167], v10 offset:18432
	v_add_f32_dpp v146, v146, v146 quad_perm:[1,0,3,2] row_mask:0xf bank_mask:0xf bound_ctrl:1
	v_pk_mul_f32 v[180:181], v[138:139], v[180:181]
	v_pk_fma_f32 v[180:181], v[140:141], v[182:183], v[180:181]
	v_add_f32_dpp v146, v146, v146 quad_perm:[2,3,0,1] row_mask:0xf bank_mask:0xf bound_ctrl:1
	v_add_f32 v156, v180, v181
	s_waitcnt lgkmcnt(12)
	v_add_f32_dpp v146, v146, v146 row_half_mirror row_mask:0xf bank_mask:0xf bound_ctrl:1
	v_pk_mul_f32 v[198:199], v[198:199], v[206:207] op_sel_hi:[1,0]
	v_pk_mul_f32 v[200:201], v[200:201], v[206:207] op_sel_hi:[1,0]
	v_add_f32_dpp v146, v146, v146 row_mirror row_mask:0xf bank_mask:0xf bound_ctrl:1
	v_pk_fma_f32 v[198:199], v[146:147], v[190:191], v[198:199] op_sel_hi:[0,1,1] neg_lo:[1,0,0] neg_hi:[1,0,0]
	v_pk_fma_f32 v[200:201], v[146:147], v[192:193], v[200:201] op_sel_hi:[0,1,1] neg_lo:[1,0,0] neg_hi:[1,0,0]
	v_pk_fma_f32 v[138:139], v[138:139], v[194:195], v[198:199]
	v_pk_fma_f32 v[140:141], v[140:141], v[196:197], v[200:201]
	v_pk_mul_f32 v[144:145], v[138:139], v[208:209]
	v_pk_fma_f32 v[144:145], v[140:141], v[210:211], v[144:145]
	v_add_f32 v146, v144, v145
	ds_read_b128 v[168:171], v10 offset:18688
	ds_read_b128 v[172:175], v10 offset:18944
	ds_read_b128 v[176:179], v10 offset:19200
	ds_read_b128 v[180:183], v10 offset:19456
	ds_read_b32 v184, v11 offset:18432
	ds_read_b128 v[186:189], v10 offset:19968
	v_add_f32_dpp v146, v146, v146 quad_perm:[1,0,3,2] row_mask:0xf bank_mask:0xf bound_ctrl:1
	v_pk_mul_f32 v[202:203], v[138:139], v[202:203]
	v_pk_fma_f32 v[202:203], v[140:141], v[204:205], v[202:203]
	v_add_f32_dpp v146, v146, v146 quad_perm:[2,3,0,1] row_mask:0xf bank_mask:0xf bound_ctrl:1
	v_add_f32 v157, v202, v203
	s_waitcnt lgkmcnt(12)
	v_add_f32_dpp v146, v146, v146 row_half_mirror row_mask:0xf bank_mask:0xf bound_ctrl:1
	v_pk_mul_f32 v[220:221], v[220:221], v[228:229] op_sel_hi:[1,0]
	v_pk_mul_f32 v[222:223], v[222:223], v[228:229] op_sel_hi:[1,0]
	v_add_f32_dpp v146, v146, v146 row_mirror row_mask:0xf bank_mask:0xf bound_ctrl:1
	v_pk_fma_f32 v[220:221], v[146:147], v[212:213], v[220:221] op_sel_hi:[0,1,1] neg_lo:[1,0,0] neg_hi:[1,0,0]
	v_pk_fma_f32 v[222:223], v[146:147], v[214:215], v[222:223] op_sel_hi:[0,1,1] neg_lo:[1,0,0] neg_hi:[1,0,0]
	v_pk_fma_f32 v[138:139], v[138:139], v[216:217], v[220:221]
	v_pk_fma_f32 v[140:141], v[140:141], v[218:219], v[222:223]
	v_pk_mul_f32 v[144:145], v[138:139], v[230:231]
	v_pk_fma_f32 v[144:145], v[140:141], v[232:233], v[144:145]
	v_add_f32 v146, v144, v145
	ds_read_b128 v[190:193], v10 offset:20224
	ds_read_b128 v[194:197], v10 offset:20480
	ds_read_b128 v[198:201], v10 offset:20736
	ds_read_b128 v[202:205], v10 offset:20992
	ds_read_b32 v206, v11 offset:19968
	ds_read_b128 v[208:211], v10 offset:21504
	v_add_f32_dpp v146, v146, v146 quad_perm:[1,0,3,2] row_mask:0xf bank_mask:0xf bound_ctrl:1
	v_pk_mul_f32 v[224:225], v[138:139], v[224:225]
	v_pk_fma_f32 v[224:225], v[140:141], v[226:227], v[224:225]
	v_add_f32_dpp v146, v146, v146 quad_perm:[2,3,0,1] row_mask:0xf bank_mask:0xf bound_ctrl:1
	v_add_f32 v158, v224, v225
	s_waitcnt lgkmcnt(12)
	v_add_f32_dpp v146, v146, v146 row_half_mirror row_mask:0xf bank_mask:0xf bound_ctrl:1
	v_pk_mul_f32 v[242:243], v[242:243], v[250:251] op_sel_hi:[1,0]
	v_pk_mul_f32 v[244:245], v[244:245], v[250:251] op_sel_hi:[1,0]
	v_add_f32_dpp v146, v146, v146 row_mirror row_mask:0xf bank_mask:0xf bound_ctrl:1
	v_pk_fma_f32 v[242:243], v[146:147], v[234:235], v[242:243] op_sel_hi:[0,1,1] neg_lo:[1,0,0] neg_hi:[1,0,0]
	v_pk_fma_f32 v[244:245], v[146:147], v[236:237], v[244:245] op_sel_hi:[0,1,1] neg_lo:[1,0,0] neg_hi:[1,0,0]
	v_pk_fma_f32 v[138:139], v[138:139], v[238:239], v[242:243]
	v_pk_fma_f32 v[140:141], v[140:141], v[240:241], v[244:245]
	v_pk_mul_f32 v[144:145], v[138:139], v[164:165]
	v_pk_fma_f32 v[144:145], v[140:141], v[166:167], v[144:145]
	v_add_f32 v146, v144, v145
	ds_read_b128 v[212:215], v10 offset:21760
	ds_read_b128 v[216:219], v10 offset:22016
	ds_read_b128 v[220:223], v10 offset:22272
	ds_read_b128 v[224:227], v10 offset:22528
	ds_read_b32 v228, v11 offset:21504
	ds_read_b128 v[230:233], v10 offset:23040
	v_add_f32_dpp v146, v146, v146 quad_perm:[1,0,3,2] row_mask:0xf bank_mask:0xf bound_ctrl:1
	v_pk_mul_f32 v[246:247], v[138:139], v[246:247]
	v_pk_fma_f32 v[246:247], v[140:141], v[248:249], v[246:247]
	v_add_f32_dpp v146, v146, v146 quad_perm:[2,3,0,1] row_mask:0xf bank_mask:0xf bound_ctrl:1
	v_add_f32 v159, v246, v247
	s_waitcnt lgkmcnt(12)
	v_add_f32_dpp v146, v146, v146 row_half_mirror row_mask:0xf bank_mask:0xf bound_ctrl:1
	v_pk_mul_f32 v[176:177], v[176:177], v[184:185] op_sel_hi:[1,0]
	v_pk_mul_f32 v[178:179], v[178:179], v[184:185] op_sel_hi:[1,0]
	v_add_f32_dpp v146, v146, v146 row_mirror row_mask:0xf bank_mask:0xf bound_ctrl:1
	v_pk_fma_f32 v[176:177], v[146:147], v[168:169], v[176:177] op_sel_hi:[0,1,1] neg_lo:[1,0,0] neg_hi:[1,0,0]
	v_pk_fma_f32 v[178:179], v[146:147], v[170:171], v[178:179] op_sel_hi:[0,1,1] neg_lo:[1,0,0] neg_hi:[1,0,0]
	v_pk_fma_f32 v[138:139], v[138:139], v[172:173], v[176:177]
	v_pk_fma_f32 v[140:141], v[140:141], v[174:175], v[178:179]
	v_pk_mul_f32 v[144:145], v[138:139], v[186:187]
	v_pk_fma_f32 v[144:145], v[140:141], v[188:189], v[144:145]
	v_add_f32 v146, v144, v145
	ds_read_b128 v[234:237], v10 offset:23296
	ds_read_b128 v[238:241], v10 offset:23552
	ds_read_b128 v[242:245], v10 offset:23808
	ds_read_b128 v[246:249], v10 offset:24064
	ds_read_b32 v250, v11 offset:23040
	ds_read_b128 v[164:167], v10 offset:24576
	v_add_f32_dpp v146, v146, v146 quad_perm:[1,0,3,2] row_mask:0xf bank_mask:0xf bound_ctrl:1
	v_pk_mul_f32 v[180:181], v[138:139], v[180:181]
	v_pk_fma_f32 v[180:181], v[140:141], v[182:183], v[180:181]
	v_add_f32_dpp v146, v146, v146 quad_perm:[2,3,0,1] row_mask:0xf bank_mask:0xf bound_ctrl:1
	v_add_f32 v160, v180, v181
	s_waitcnt lgkmcnt(12)
	v_add_f32_dpp v146, v146, v146 row_half_mirror row_mask:0xf bank_mask:0xf bound_ctrl:1
	v_pk_mul_f32 v[198:199], v[198:199], v[206:207] op_sel_hi:[1,0]
	v_pk_mul_f32 v[200:201], v[200:201], v[206:207] op_sel_hi:[1,0]
	v_add_f32_dpp v146, v146, v146 row_mirror row_mask:0xf bank_mask:0xf bound_ctrl:1
	v_pk_fma_f32 v[198:199], v[146:147], v[190:191], v[198:199] op_sel_hi:[0,1,1] neg_lo:[1,0,0] neg_hi:[1,0,0]
	v_pk_fma_f32 v[200:201], v[146:147], v[192:193], v[200:201] op_sel_hi:[0,1,1] neg_lo:[1,0,0] neg_hi:[1,0,0]
	v_pk_fma_f32 v[138:139], v[138:139], v[194:195], v[198:199]
	v_pk_fma_f32 v[140:141], v[140:141], v[196:197], v[200:201]
	v_pk_mul_f32 v[144:145], v[138:139], v[208:209]
	v_pk_fma_f32 v[144:145], v[140:141], v[210:211], v[144:145]
	v_add_f32 v146, v144, v145
	ds_read_b128 v[168:171], v10 offset:24832
	ds_read_b128 v[172:175], v10 offset:25088
	ds_read_b128 v[176:179], v10 offset:25344
	ds_read_b128 v[180:183], v10 offset:25600
	ds_read_b32 v184, v11 offset:24576
	ds_read_b128 v[186:189], v10 offset:26112
	v_add_f32_dpp v146, v146, v146 quad_perm:[1,0,3,2] row_mask:0xf bank_mask:0xf bound_ctrl:1
	v_pk_mul_f32 v[202:203], v[138:139], v[202:203]
	v_pk_fma_f32 v[202:203], v[140:141], v[204:205], v[202:203]
	v_add_f32_dpp v146, v146, v146 quad_perm:[2,3,0,1] row_mask:0xf bank_mask:0xf bound_ctrl:1
	v_add_f32 v161, v202, v203
	s_waitcnt lgkmcnt(12)
	v_add_f32_dpp v146, v146, v146 row_half_mirror row_mask:0xf bank_mask:0xf bound_ctrl:1
	v_pk_mul_f32 v[220:221], v[220:221], v[228:229] op_sel_hi:[1,0]
	v_pk_mul_f32 v[222:223], v[222:223], v[228:229] op_sel_hi:[1,0]
	v_add_f32_dpp v146, v146, v146 row_mirror row_mask:0xf bank_mask:0xf bound_ctrl:1
	v_pk_fma_f32 v[220:221], v[146:147], v[212:213], v[220:221] op_sel_hi:[0,1,1] neg_lo:[1,0,0] neg_hi:[1,0,0]
	v_pk_fma_f32 v[222:223], v[146:147], v[214:215], v[222:223] op_sel_hi:[0,1,1] neg_lo:[1,0,0] neg_hi:[1,0,0]
	v_pk_fma_f32 v[138:139], v[138:139], v[216:217], v[220:221]
	v_pk_fma_f32 v[140:141], v[140:141], v[218:219], v[222:223]
	v_pk_mul_f32 v[144:145], v[138:139], v[230:231]
	v_pk_fma_f32 v[144:145], v[140:141], v[232:233], v[144:145]
	v_add_f32 v146, v144, v145
	ds_read_b128 v[190:193], v10 offset:26368
	ds_read_b128 v[194:197], v10 offset:26624
	ds_read_b128 v[198:201], v10 offset:26880
	ds_read_b128 v[202:205], v10 offset:27136
	ds_read_b32 v206, v11 offset:26112
	ds_read_b128 v[208:211], v10 offset:27648
	v_add_f32_dpp v146, v146, v146 quad_perm:[1,0,3,2] row_mask:0xf bank_mask:0xf bound_ctrl:1
	v_pk_mul_f32 v[224:225], v[138:139], v[224:225]
	v_pk_fma_f32 v[224:225], v[140:141], v[226:227], v[224:225]
	v_add_f32_dpp v146, v146, v146 quad_perm:[2,3,0,1] row_mask:0xf bank_mask:0xf bound_ctrl:1
	v_add_f32 v162, v224, v225
	s_waitcnt lgkmcnt(12)
	v_add_f32_dpp v146, v146, v146 row_half_mirror row_mask:0xf bank_mask:0xf bound_ctrl:1
	v_pk_mul_f32 v[242:243], v[242:243], v[250:251] op_sel_hi:[1,0]
	v_pk_mul_f32 v[244:245], v[244:245], v[250:251] op_sel_hi:[1,0]
	v_add_f32_dpp v146, v146, v146 row_mirror row_mask:0xf bank_mask:0xf bound_ctrl:1
	v_pk_fma_f32 v[242:243], v[146:147], v[234:235], v[242:243] op_sel_hi:[0,1,1] neg_lo:[1,0,0] neg_hi:[1,0,0]
	v_pk_fma_f32 v[244:245], v[146:147], v[236:237], v[244:245] op_sel_hi:[0,1,1] neg_lo:[1,0,0] neg_hi:[1,0,0]
	v_pk_fma_f32 v[138:139], v[138:139], v[238:239], v[242:243]
	v_pk_fma_f32 v[140:141], v[140:141], v[240:241], v[244:245]
	v_pk_mul_f32 v[144:145], v[138:139], v[164:165]
	v_pk_fma_f32 v[144:145], v[140:141], v[166:167], v[144:145]
	v_add_f32 v146, v144, v145
	ds_read_b128 v[212:215], v10 offset:27904
	ds_read_b128 v[216:219], v10 offset:28160
	ds_read_b128 v[220:223], v10 offset:28416
	ds_read_b128 v[224:227], v10 offset:28672
	ds_read_b32 v228, v11 offset:27648
	ds_read_b128 v[230:233], v10 offset:29184
	v_add_f32_dpp v146, v146, v146 quad_perm:[1,0,3,2] row_mask:0xf bank_mask:0xf bound_ctrl:1
	v_pk_mul_f32 v[246:247], v[138:139], v[246:247]
	v_pk_fma_f32 v[246:247], v[140:141], v[248:249], v[246:247]
	v_add_f32_dpp v146, v146, v146 quad_perm:[2,3,0,1] row_mask:0xf bank_mask:0xf bound_ctrl:1
	v_add_f32 v163, v246, v247
	s_waitcnt lgkmcnt(12)
	v_add_f32_dpp v146, v146, v146 row_half_mirror row_mask:0xf bank_mask:0xf bound_ctrl:1
	v_pk_mul_f32 v[176:177], v[176:177], v[184:185] op_sel_hi:[1,0]
	v_pk_mul_f32 v[178:179], v[178:179], v[184:185] op_sel_hi:[1,0]
	v_add_f32_dpp v146, v146, v146 row_mirror row_mask:0xf bank_mask:0xf bound_ctrl:1
	v_pk_fma_f32 v[176:177], v[146:147], v[168:169], v[176:177] op_sel_hi:[0,1,1] neg_lo:[1,0,0] neg_hi:[1,0,0]
	v_pk_fma_f32 v[178:179], v[146:147], v[170:171], v[178:179] op_sel_hi:[0,1,1] neg_lo:[1,0,0] neg_hi:[1,0,0]
	v_pk_fma_f32 v[138:139], v[138:139], v[172:173], v[176:177]
	v_pk_fma_f32 v[140:141], v[140:141], v[174:175], v[178:179]
	v_pk_mul_f32 v[144:145], v[138:139], v[186:187]
	v_pk_fma_f32 v[144:145], v[140:141], v[188:189], v[144:145]
	v_add_f32 v146, v144, v145
	v_add_f32_dpp v102, v148, v148 row_mirror row_mask:0xf bank_mask:0x3 bound_ctrl:1
	v_add_f32_dpp v102, v156, v156 row_mirror row_mask:0xf bank_mask:0xc bound_ctrl:1
	v_add_f32_dpp v103, v149, v149 row_mirror row_mask:0xf bank_mask:0x3 bound_ctrl:1
	v_add_f32_dpp v103, v157, v157 row_mirror row_mask:0xf bank_mask:0xc bound_ctrl:1
	v_add_f32_dpp v104, v150, v150 row_mirror row_mask:0xf bank_mask:0x3 bound_ctrl:1
	v_add_f32_dpp v104, v158, v158 row_mirror row_mask:0xf bank_mask:0xc bound_ctrl:1
	v_add_f32_dpp v105, v151, v151 row_mirror row_mask:0xf bank_mask:0x3 bound_ctrl:1
	v_add_f32_dpp v105, v159, v159 row_mirror row_mask:0xf bank_mask:0xc bound_ctrl:1
	v_add_f32_dpp v106, v152, v152 row_mirror row_mask:0xf bank_mask:0x3 bound_ctrl:1
	v_add_f32_dpp v106, v160, v160 row_mirror row_mask:0xf bank_mask:0xc bound_ctrl:1
	v_add_f32_dpp v107, v153, v153 row_mirror row_mask:0xf bank_mask:0x3 bound_ctrl:1
	v_add_f32_dpp v107, v161, v161 row_mirror row_mask:0xf bank_mask:0xc bound_ctrl:1
	v_add_f32_dpp v108, v154, v154 row_mirror row_mask:0xf bank_mask:0x3 bound_ctrl:1
	v_add_f32_dpp v108, v162, v162 row_mirror row_mask:0xf bank_mask:0xc bound_ctrl:1
	v_add_f32_dpp v109, v155, v155 row_mirror row_mask:0xf bank_mask:0x3 bound_ctrl:1
	v_add_f32_dpp v109, v163, v163 row_mirror row_mask:0xf bank_mask:0xc bound_ctrl:1
	v_add_f32_dpp v110, v102, v102 row_half_mirror row_mask:0xf bank_mask:0x5 bound_ctrl:1
	v_add_f32_dpp v110, v106, v106 row_half_mirror row_mask:0xf bank_mask:0xa bound_ctrl:1
	v_add_f32_dpp v111, v103, v103 row_half_mirror row_mask:0xf bank_mask:0x5 bound_ctrl:1
	v_add_f32_dpp v111, v107, v107 row_half_mirror row_mask:0xf bank_mask:0xa bound_ctrl:1
	v_add_f32_dpp v112, v104, v104 row_half_mirror row_mask:0xf bank_mask:0x5 bound_ctrl:1
	v_add_f32_dpp v112, v108, v108 row_half_mirror row_mask:0xf bank_mask:0xa bound_ctrl:1
	v_add_f32_dpp v113, v105, v105 row_half_mirror row_mask:0xf bank_mask:0x5 bound_ctrl:1
	v_add_f32_dpp v113, v109, v109 row_half_mirror row_mask:0xf bank_mask:0xa bound_ctrl:1
	s_mov_b32 vcc_lo, 0xcccccccc
	s_mov_b32 vcc_hi, 0xcccccccc
	v_cndmask_b32 v116, v112, v110, vcc
	v_cndmask_b32 v117, v113, v111, vcc
	v_cndmask_b32 v114, v110, v112, vcc
	v_cndmask_b32 v115, v111, v113, vcc
	v_add_f32_dpp v114, v116, v114 quad_perm:[2,3,0,1] row_mask:0xf bank_mask:0xf bound_ctrl:1
	v_add_f32_dpp v115, v117, v115 quad_perm:[2,3,0,1] row_mask:0xf bank_mask:0xf bound_ctrl:1
	s_mov_b32 vcc_lo, 0xaaaaaaaa
	s_mov_b32 vcc_hi, 0xaaaaaaaa
	v_cndmask_b32 v116, v115, v114, vcc
	v_cndmask_b32 v117, v114, v115, vcc
	s_nop 0
	v_add_f32_dpp v18, v116, v117 quad_perm:[1,0,3,2] row_mask:0xf bank_mask:0xf bound_ctrl:1
	ds_read_b128 v[234:237], v10 offset:29440
	ds_read_b128 v[238:241], v10 offset:29696
	ds_read_b128 v[242:245], v10 offset:29952
	ds_read_b128 v[246:249], v10 offset:30208
	ds_read_b32 v250, v11 offset:29184
	ds_read_b128 v[164:167], v10 offset:30720
	v_add_f32_dpp v146, v146, v146 quad_perm:[1,0,3,2] row_mask:0xf bank_mask:0xf bound_ctrl:1
	v_pk_mul_f32 v[180:181], v[138:139], v[180:181]
	v_pk_fma_f32 v[180:181], v[140:141], v[182:183], v[180:181]
	v_add_f32_dpp v146, v146, v146 quad_perm:[2,3,0,1] row_mask:0xf bank_mask:0xf bound_ctrl:1
	v_add_f32 v148, v180, v181
	s_waitcnt lgkmcnt(12)
	v_add_f32_dpp v146, v146, v146 row_half_mirror row_mask:0xf bank_mask:0xf bound_ctrl:1
	v_pk_mul_f32 v[198:199], v[198:199], v[206:207] op_sel_hi:[1,0]
	v_pk_mul_f32 v[200:201], v[200:201], v[206:207] op_sel_hi:[1,0]
	v_add_f32_dpp v146, v146, v146 row_mirror row_mask:0xf bank_mask:0xf bound_ctrl:1
	v_pk_fma_f32 v[198:199], v[146:147], v[190:191], v[198:199] op_sel_hi:[0,1,1] neg_lo:[1,0,0] neg_hi:[1,0,0]
	v_pk_fma_f32 v[200:201], v[146:147], v[192:193], v[200:201] op_sel_hi:[0,1,1] neg_lo:[1,0,0] neg_hi:[1,0,0]
	v_pk_fma_f32 v[138:139], v[138:139], v[194:195], v[198:199]
	v_pk_fma_f32 v[140:141], v[140:141], v[196:197], v[200:201]
	v_pk_mul_f32 v[144:145], v[138:139], v[208:209]
	v_pk_fma_f32 v[144:145], v[140:141], v[210:211], v[144:145]
	v_add_f32 v146, v144, v145
	ds_read_b128 v[168:171], v10 offset:30976
	ds_read_b128 v[172:175], v10 offset:31232
	ds_read_b128 v[176:179], v10 offset:31488
	ds_read_b128 v[180:183], v10 offset:31744
	ds_read_b32 v184, v11 offset:30720
	ds_read_b128 v[186:189], v10 offset:32256
	v_add_f32_dpp v146, v146, v146 quad_perm:[1,0,3,2] row_mask:0xf bank_mask:0xf bound_ctrl:1
	v_pk_mul_f32 v[202:203], v[138:139], v[202:203]
	v_pk_fma_f32 v[202:203], v[140:141], v[204:205], v[202:203]
	v_add_f32_dpp v146, v146, v146 quad_perm:[2,3,0,1] row_mask:0xf bank_mask:0xf bound_ctrl:1
	v_add_f32 v149, v202, v203
	s_waitcnt lgkmcnt(12)
	v_add_f32_dpp v146, v146, v146 row_half_mirror row_mask:0xf bank_mask:0xf bound_ctrl:1
	v_pk_mul_f32 v[220:221], v[220:221], v[228:229] op_sel_hi:[1,0]
	v_pk_mul_f32 v[222:223], v[222:223], v[228:229] op_sel_hi:[1,0]
	v_add_f32_dpp v146, v146, v146 row_mirror row_mask:0xf bank_mask:0xf bound_ctrl:1
	v_pk_fma_f32 v[220:221], v[146:147], v[212:213], v[220:221] op_sel_hi:[0,1,1] neg_lo:[1,0,0] neg_hi:[1,0,0]
	v_pk_fma_f32 v[222:223], v[146:147], v[214:215], v[222:223] op_sel_hi:[0,1,1] neg_lo:[1,0,0] neg_hi:[1,0,0]
	v_pk_fma_f32 v[138:139], v[138:139], v[216:217], v[220:221]
	v_pk_fma_f32 v[140:141], v[140:141], v[218:219], v[222:223]
	v_pk_mul_f32 v[144:145], v[138:139], v[230:231]
	v_pk_fma_f32 v[144:145], v[140:141], v[232:233], v[144:145]
	v_add_f32 v146, v144, v145
	ds_read_b128 v[190:193], v10 offset:32512
	ds_read_b128 v[194:197], v10 offset:32768
	ds_read_b128 v[198:201], v10 offset:33024
	ds_read_b128 v[202:205], v10 offset:33280
	ds_read_b32 v206, v11 offset:32256
	ds_read_b128 v[208:211], v10 offset:33792
	v_add_f32_dpp v146, v146, v146 quad_perm:[1,0,3,2] row_mask:0xf bank_mask:0xf bound_ctrl:1
	v_pk_mul_f32 v[224:225], v[138:139], v[224:225]
	v_pk_fma_f32 v[224:225], v[140:141], v[226:227], v[224:225]
	v_add_f32_dpp v146, v146, v146 quad_perm:[2,3,0,1] row_mask:0xf bank_mask:0xf bound_ctrl:1
	v_add_f32 v150, v224, v225
	s_waitcnt lgkmcnt(12)
	v_add_f32_dpp v146, v146, v146 row_half_mirror row_mask:0xf bank_mask:0xf bound_ctrl:1
	v_pk_mul_f32 v[242:243], v[242:243], v[250:251] op_sel_hi:[1,0]
	v_pk_mul_f32 v[244:245], v[244:245], v[250:251] op_sel_hi:[1,0]
	v_add_f32_dpp v146, v146, v146 row_mirror row_mask:0xf bank_mask:0xf bound_ctrl:1
	v_pk_fma_f32 v[242:243], v[146:147], v[234:235], v[242:243] op_sel_hi:[0,1,1] neg_lo:[1,0,0] neg_hi:[1,0,0]
	v_pk_fma_f32 v[244:245], v[146:147], v[236:237], v[244:245] op_sel_hi:[0,1,1] neg_lo:[1,0,0] neg_hi:[1,0,0]
	v_pk_fma_f32 v[138:139], v[138:139], v[238:239], v[242:243]
	v_pk_fma_f32 v[140:141], v[140:141], v[240:241], v[244:245]
	v_pk_mul_f32 v[144:145], v[138:139], v[164:165]
	v_pk_fma_f32 v[144:145], v[140:141], v[166:167], v[144:145]
	v_add_f32 v146, v144, v145
	ds_read_b128 v[212:215], v10 offset:34048
	ds_read_b128 v[216:219], v10 offset:34304
	ds_read_b128 v[220:223], v10 offset:34560
	ds_read_b128 v[224:227], v10 offset:34816
	ds_read_b32 v228, v11 offset:33792
	ds_read_b128 v[230:233], v10 offset:35328
	v_add_f32_dpp v146, v146, v146 quad_perm:[1,0,3,2] row_mask:0xf bank_mask:0xf bound_ctrl:1
	v_pk_mul_f32 v[246:247], v[138:139], v[246:247]
	v_pk_fma_f32 v[246:247], v[140:141], v[248:249], v[246:247]
	v_add_f32_dpp v146, v146, v146 quad_perm:[2,3,0,1] row_mask:0xf bank_mask:0xf bound_ctrl:1
	v_add_f32 v151, v246, v247
	s_waitcnt lgkmcnt(12)
	v_add_f32_dpp v146, v146, v146 row_half_mirror row_mask:0xf bank_mask:0xf bound_ctrl:1
	v_pk_mul_f32 v[176:177], v[176:177], v[184:185] op_sel_hi:[1,0]
	v_pk_mul_f32 v[178:179], v[178:179], v[184:185] op_sel_hi:[1,0]
	v_add_f32_dpp v146, v146, v146 row_mirror row_mask:0xf bank_mask:0xf bound_ctrl:1
	v_pk_fma_f32 v[176:177], v[146:147], v[168:169], v[176:177] op_sel_hi:[0,1,1] neg_lo:[1,0,0] neg_hi:[1,0,0]
	v_pk_fma_f32 v[178:179], v[146:147], v[170:171], v[178:179] op_sel_hi:[0,1,1] neg_lo:[1,0,0] neg_hi:[1,0,0]
	v_pk_fma_f32 v[138:139], v[138:139], v[172:173], v[176:177]
	v_pk_fma_f32 v[140:141], v[140:141], v[174:175], v[178:179]
	v_pk_mul_f32 v[144:145], v[138:139], v[186:187]
	v_pk_fma_f32 v[144:145], v[140:141], v[188:189], v[144:145]
	v_add_f32 v146, v144, v145
	ds_read_b128 v[234:237], v10 offset:35584
	ds_read_b128 v[238:241], v10 offset:35840
	ds_read_b128 v[242:245], v10 offset:36096
	ds_read_b128 v[246:249], v10 offset:36352
	ds_read_b32 v250, v11 offset:35328
	ds_read_b128 v[164:167], v10 offset:36864
	v_add_f32_dpp v146, v146, v146 quad_perm:[1,0,3,2] row_mask:0xf bank_mask:0xf bound_ctrl:1
	v_pk_mul_f32 v[180:181], v[138:139], v[180:181]
	v_pk_fma_f32 v[180:181], v[140:141], v[182:183], v[180:181]
	v_add_f32_dpp v146, v146, v146 quad_perm:[2,3,0,1] row_mask:0xf bank_mask:0xf bound_ctrl:1
	v_add_f32 v152, v180, v181
	s_waitcnt lgkmcnt(12)
	v_add_f32_dpp v146, v146, v146 row_half_mirror row_mask:0xf bank_mask:0xf bound_ctrl:1
	v_pk_mul_f32 v[198:199], v[198:199], v[206:207] op_sel_hi:[1,0]
	v_pk_mul_f32 v[200:201], v[200:201], v[206:207] op_sel_hi:[1,0]
	v_add_f32_dpp v146, v146, v146 row_mirror row_mask:0xf bank_mask:0xf bound_ctrl:1
	v_pk_fma_f32 v[198:199], v[146:147], v[190:191], v[198:199] op_sel_hi:[0,1,1] neg_lo:[1,0,0] neg_hi:[1,0,0]
	v_pk_fma_f32 v[200:201], v[146:147], v[192:193], v[200:201] op_sel_hi:[0,1,1] neg_lo:[1,0,0] neg_hi:[1,0,0]
	v_pk_fma_f32 v[138:139], v[138:139], v[194:195], v[198:199]
	v_pk_fma_f32 v[140:141], v[140:141], v[196:197], v[200:201]
	v_pk_mul_f32 v[144:145], v[138:139], v[208:209]
	v_pk_fma_f32 v[144:145], v[140:141], v[210:211], v[144:145]
	v_add_f32 v146, v144, v145
	ds_read_b128 v[168:171], v10 offset:37120
	ds_read_b128 v[172:175], v10 offset:37376
	ds_read_b128 v[176:179], v10 offset:37632
	ds_read_b128 v[180:183], v10 offset:37888
	ds_read_b32 v184, v11 offset:36864
	ds_read_b128 v[186:189], v10 offset:38400
	v_add_f32_dpp v146, v146, v146 quad_perm:[1,0,3,2] row_mask:0xf bank_mask:0xf bound_ctrl:1
	v_pk_mul_f32 v[202:203], v[138:139], v[202:203]
	v_pk_fma_f32 v[202:203], v[140:141], v[204:205], v[202:203]
	v_add_f32_dpp v146, v146, v146 quad_perm:[2,3,0,1] row_mask:0xf bank_mask:0xf bound_ctrl:1
	v_add_f32 v153, v202, v203
	s_waitcnt lgkmcnt(12)
	v_add_f32_dpp v146, v146, v146 row_half_mirror row_mask:0xf bank_mask:0xf bound_ctrl:1
	v_pk_mul_f32 v[220:221], v[220:221], v[228:229] op_sel_hi:[1,0]
	v_pk_mul_f32 v[222:223], v[222:223], v[228:229] op_sel_hi:[1,0]
	v_add_f32_dpp v146, v146, v146 row_mirror row_mask:0xf bank_mask:0xf bound_ctrl:1
	v_pk_fma_f32 v[220:221], v[146:147], v[212:213], v[220:221] op_sel_hi:[0,1,1] neg_lo:[1,0,0] neg_hi:[1,0,0]
	v_pk_fma_f32 v[222:223], v[146:147], v[214:215], v[222:223] op_sel_hi:[0,1,1] neg_lo:[1,0,0] neg_hi:[1,0,0]
	v_pk_fma_f32 v[138:139], v[138:139], v[216:217], v[220:221]
	v_pk_fma_f32 v[140:141], v[140:141], v[218:219], v[222:223]
	v_pk_mul_f32 v[144:145], v[138:139], v[230:231]
	v_pk_fma_f32 v[144:145], v[140:141], v[232:233], v[144:145]
	v_add_f32 v146, v144, v145
	ds_read_b128 v[190:193], v10 offset:38656
	ds_read_b128 v[194:197], v10 offset:38912
	ds_read_b128 v[198:201], v10 offset:39168
	ds_read_b128 v[202:205], v10 offset:39424
	ds_read_b32 v206, v11 offset:38400
	ds_read_b128 v[208:211], v10 offset:39936
	v_add_f32_dpp v146, v146, v146 quad_perm:[1,0,3,2] row_mask:0xf bank_mask:0xf bound_ctrl:1
	v_pk_mul_f32 v[224:225], v[138:139], v[224:225]
	v_pk_fma_f32 v[224:225], v[140:141], v[226:227], v[224:225]
	v_add_f32_dpp v146, v146, v146 quad_perm:[2,3,0,1] row_mask:0xf bank_mask:0xf bound_ctrl:1
	v_add_f32 v154, v224, v225
	s_waitcnt lgkmcnt(12)
	v_add_f32_dpp v146, v146, v146 row_half_mirror row_mask:0xf bank_mask:0xf bound_ctrl:1
	v_pk_mul_f32 v[242:243], v[242:243], v[250:251] op_sel_hi:[1,0]
	v_pk_mul_f32 v[244:245], v[244:245], v[250:251] op_sel_hi:[1,0]
	v_add_f32_dpp v146, v146, v146 row_mirror row_mask:0xf bank_mask:0xf bound_ctrl:1
	v_pk_fma_f32 v[242:243], v[146:147], v[234:235], v[242:243] op_sel_hi:[0,1,1] neg_lo:[1,0,0] neg_hi:[1,0,0]
	v_pk_fma_f32 v[244:245], v[146:147], v[236:237], v[244:245] op_sel_hi:[0,1,1] neg_lo:[1,0,0] neg_hi:[1,0,0]
	v_pk_fma_f32 v[138:139], v[138:139], v[238:239], v[242:243]
	v_pk_fma_f32 v[140:141], v[140:141], v[240:241], v[244:245]
	v_pk_mul_f32 v[144:145], v[138:139], v[164:165]
	v_pk_fma_f32 v[144:145], v[140:141], v[166:167], v[144:145]
	v_add_f32 v146, v144, v145
	ds_read_b128 v[212:215], v10 offset:40192
	ds_read_b128 v[216:219], v10 offset:40448
	ds_read_b128 v[220:223], v10 offset:40704
	ds_read_b128 v[224:227], v10 offset:40960
	ds_read_b32 v228, v11 offset:39936
	ds_read_b128 v[230:233], v10 offset:41472
	v_add_f32_dpp v146, v146, v146 quad_perm:[1,0,3,2] row_mask:0xf bank_mask:0xf bound_ctrl:1
	v_pk_mul_f32 v[246:247], v[138:139], v[246:247]
	v_pk_fma_f32 v[246:247], v[140:141], v[248:249], v[246:247]
	v_add_f32_dpp v146, v146, v146 quad_perm:[2,3,0,1] row_mask:0xf bank_mask:0xf bound_ctrl:1
	v_add_f32 v155, v246, v247
	s_waitcnt lgkmcnt(12)
	v_add_f32_dpp v146, v146, v146 row_half_mirror row_mask:0xf bank_mask:0xf bound_ctrl:1
	v_pk_mul_f32 v[176:177], v[176:177], v[184:185] op_sel_hi:[1,0]
	v_pk_mul_f32 v[178:179], v[178:179], v[184:185] op_sel_hi:[1,0]
	v_add_f32_dpp v146, v146, v146 row_mirror row_mask:0xf bank_mask:0xf bound_ctrl:1
	v_pk_fma_f32 v[176:177], v[146:147], v[168:169], v[176:177] op_sel_hi:[0,1,1] neg_lo:[1,0,0] neg_hi:[1,0,0]
	v_pk_fma_f32 v[178:179], v[146:147], v[170:171], v[178:179] op_sel_hi:[0,1,1] neg_lo:[1,0,0] neg_hi:[1,0,0]
	v_pk_fma_f32 v[138:139], v[138:139], v[172:173], v[176:177]
	v_pk_fma_f32 v[140:141], v[140:141], v[174:175], v[178:179]
	v_pk_mul_f32 v[144:145], v[138:139], v[186:187]
	v_pk_fma_f32 v[144:145], v[140:141], v[188:189], v[144:145]
	v_add_f32 v146, v144, v145
	ds_read_b128 v[234:237], v10 offset:41728
	ds_read_b128 v[238:241], v10 offset:41984
	ds_read_b128 v[242:245], v10 offset:42240
	ds_read_b128 v[246:249], v10 offset:42496
	ds_read_b32 v250, v11 offset:41472
	ds_read_b128 v[164:167], v10 offset:43008
	v_add_f32_dpp v146, v146, v146 quad_perm:[1,0,3,2] row_mask:0xf bank_mask:0xf bound_ctrl:1
	v_pk_mul_f32 v[180:181], v[138:139], v[180:181]
	v_pk_fma_f32 v[180:181], v[140:141], v[182:183], v[180:181]
	v_add_f32_dpp v146, v146, v146 quad_perm:[2,3,0,1] row_mask:0xf bank_mask:0xf bound_ctrl:1
	v_add_f32 v156, v180, v181
	s_waitcnt lgkmcnt(12)
	v_add_f32_dpp v146, v146, v146 row_half_mirror row_mask:0xf bank_mask:0xf bound_ctrl:1
	v_pk_mul_f32 v[198:199], v[198:199], v[206:207] op_sel_hi:[1,0]
	v_pk_mul_f32 v[200:201], v[200:201], v[206:207] op_sel_hi:[1,0]
	v_add_f32_dpp v146, v146, v146 row_mirror row_mask:0xf bank_mask:0xf bound_ctrl:1
	v_pk_fma_f32 v[198:199], v[146:147], v[190:191], v[198:199] op_sel_hi:[0,1,1] neg_lo:[1,0,0] neg_hi:[1,0,0]
	v_pk_fma_f32 v[200:201], v[146:147], v[192:193], v[200:201] op_sel_hi:[0,1,1] neg_lo:[1,0,0] neg_hi:[1,0,0]
	v_pk_fma_f32 v[138:139], v[138:139], v[194:195], v[198:199]
	v_pk_fma_f32 v[140:141], v[140:141], v[196:197], v[200:201]
	v_pk_mul_f32 v[144:145], v[138:139], v[208:209]
	v_pk_fma_f32 v[144:145], v[140:141], v[210:211], v[144:145]
	v_add_f32 v146, v144, v145
	ds_read_b128 v[168:171], v10 offset:43264
	ds_read_b128 v[172:175], v10 offset:43520
	ds_read_b128 v[176:179], v10 offset:43776
	ds_read_b128 v[180:183], v10 offset:44032
	ds_read_b32 v184, v11 offset:43008
	ds_read_b128 v[186:189], v10 offset:44544
	v_add_f32_dpp v146, v146, v146 quad_perm:[1,0,3,2] row_mask:0xf bank_mask:0xf bound_ctrl:1
	v_pk_mul_f32 v[202:203], v[138:139], v[202:203]
	v_pk_fma_f32 v[202:203], v[140:141], v[204:205], v[202:203]
	v_add_f32_dpp v146, v146, v146 quad_perm:[2,3,0,1] row_mask:0xf bank_mask:0xf bound_ctrl:1
	v_add_f32 v157, v202, v203
	s_waitcnt lgkmcnt(12)
	v_add_f32_dpp v146, v146, v146 row_half_mirror row_mask:0xf bank_mask:0xf bound_ctrl:1
	v_pk_mul_f32 v[220:221], v[220:221], v[228:229] op_sel_hi:[1,0]
	v_pk_mul_f32 v[222:223], v[222:223], v[228:229] op_sel_hi:[1,0]
	v_add_f32_dpp v146, v146, v146 row_mirror row_mask:0xf bank_mask:0xf bound_ctrl:1
	v_pk_fma_f32 v[220:221], v[146:147], v[212:213], v[220:221] op_sel_hi:[0,1,1] neg_lo:[1,0,0] neg_hi:[1,0,0]
	v_pk_fma_f32 v[222:223], v[146:147], v[214:215], v[222:223] op_sel_hi:[0,1,1] neg_lo:[1,0,0] neg_hi:[1,0,0]
	v_pk_fma_f32 v[138:139], v[138:139], v[216:217], v[220:221]
	v_pk_fma_f32 v[140:141], v[140:141], v[218:219], v[222:223]
	v_pk_mul_f32 v[144:145], v[138:139], v[230:231]
	v_pk_fma_f32 v[144:145], v[140:141], v[232:233], v[144:145]
	v_add_f32 v146, v144, v145
	ds_read_b128 v[190:193], v10 offset:44800
	ds_read_b128 v[194:197], v10 offset:45056
	ds_read_b128 v[198:201], v10 offset:45312
	ds_read_b128 v[202:205], v10 offset:45568
	ds_read_b32 v206, v11 offset:44544
	ds_read_b128 v[208:211], v10 offset:46080
	v_add_f32_dpp v146, v146, v146 quad_perm:[1,0,3,2] row_mask:0xf bank_mask:0xf bound_ctrl:1
	v_pk_mul_f32 v[224:225], v[138:139], v[224:225]
	v_pk_fma_f32 v[224:225], v[140:141], v[226:227], v[224:225]
	v_add_f32_dpp v146, v146, v146 quad_perm:[2,3,0,1] row_mask:0xf bank_mask:0xf bound_ctrl:1
	v_add_f32 v158, v224, v225
	s_waitcnt lgkmcnt(12)
	v_add_f32_dpp v146, v146, v146 row_half_mirror row_mask:0xf bank_mask:0xf bound_ctrl:1
	v_pk_mul_f32 v[242:243], v[242:243], v[250:251] op_sel_hi:[1,0]
	v_pk_mul_f32 v[244:245], v[244:245], v[250:251] op_sel_hi:[1,0]
	v_add_f32_dpp v146, v146, v146 row_mirror row_mask:0xf bank_mask:0xf bound_ctrl:1
	v_pk_fma_f32 v[242:243], v[146:147], v[234:235], v[242:243] op_sel_hi:[0,1,1] neg_lo:[1,0,0] neg_hi:[1,0,0]
	v_pk_fma_f32 v[244:245], v[146:147], v[236:237], v[244:245] op_sel_hi:[0,1,1] neg_lo:[1,0,0] neg_hi:[1,0,0]
	v_pk_fma_f32 v[138:139], v[138:139], v[238:239], v[242:243]
	v_pk_fma_f32 v[140:141], v[140:141], v[240:241], v[244:245]
	v_pk_mul_f32 v[144:145], v[138:139], v[164:165]
	v_pk_fma_f32 v[144:145], v[140:141], v[166:167], v[144:145]
	v_add_f32 v146, v144, v145
	ds_read_b128 v[212:215], v10 offset:46336
	ds_read_b128 v[216:219], v10 offset:46592
	ds_read_b128 v[220:223], v10 offset:46848
	ds_read_b128 v[224:227], v10 offset:47104
	ds_read_b32 v228, v11 offset:46080
	ds_read_b128 v[230:233], v10 offset:47616
	v_add_f32_dpp v146, v146, v146 quad_perm:[1,0,3,2] row_mask:0xf bank_mask:0xf bound_ctrl:1
	v_pk_mul_f32 v[246:247], v[138:139], v[246:247]
	v_pk_fma_f32 v[246:247], v[140:141], v[248:249], v[246:247]
	v_add_f32_dpp v146, v146, v146 quad_perm:[2,3,0,1] row_mask:0xf bank_mask:0xf bound_ctrl:1
	v_add_f32 v159, v246, v247
	s_waitcnt lgkmcnt(12)
	v_add_f32_dpp v146, v146, v146 row_half_mirror row_mask:0xf bank_mask:0xf bound_ctrl:1
	v_pk_mul_f32 v[176:177], v[176:177], v[184:185] op_sel_hi:[1,0]
	v_pk_mul_f32 v[178:179], v[178:179], v[184:185] op_sel_hi:[1,0]
	v_add_f32_dpp v146, v146, v146 row_mirror row_mask:0xf bank_mask:0xf bound_ctrl:1
	v_pk_fma_f32 v[176:177], v[146:147], v[168:169], v[176:177] op_sel_hi:[0,1,1] neg_lo:[1,0,0] neg_hi:[1,0,0]
	v_pk_fma_f32 v[178:179], v[146:147], v[170:171], v[178:179] op_sel_hi:[0,1,1] neg_lo:[1,0,0] neg_hi:[1,0,0]
	v_pk_fma_f32 v[138:139], v[138:139], v[172:173], v[176:177]
	v_pk_fma_f32 v[140:141], v[140:141], v[174:175], v[178:179]
	v_pk_mul_f32 v[144:145], v[138:139], v[186:187]
	v_pk_fma_f32 v[144:145], v[140:141], v[188:189], v[144:145]
	v_add_f32 v146, v144, v145
	ds_read_b128 v[234:237], v10 offset:47872
	ds_read_b128 v[238:241], v10 offset:48128
	ds_read_b128 v[242:245], v10 offset:48384
	ds_read_b128 v[246:249], v10 offset:48640
	ds_read_b32 v250, v11 offset:47616
	v_add_f32_dpp v146, v146, v146 quad_perm:[1,0,3,2] row_mask:0xf bank_mask:0xf bound_ctrl:1
	v_pk_mul_f32 v[180:181], v[138:139], v[180:181]
	v_pk_fma_f32 v[180:181], v[140:141], v[182:183], v[180:181]
	v_add_f32_dpp v146, v146, v146 quad_perm:[2,3,0,1] row_mask:0xf bank_mask:0xf bound_ctrl:1
	v_add_f32 v160, v180, v181
	s_waitcnt lgkmcnt(11)
	v_add_f32_dpp v146, v146, v146 row_half_mirror row_mask:0xf bank_mask:0xf bound_ctrl:1
	v_pk_mul_f32 v[198:199], v[198:199], v[206:207] op_sel_hi:[1,0]
	v_pk_mul_f32 v[200:201], v[200:201], v[206:207] op_sel_hi:[1,0]
	v_add_f32_dpp v146, v146, v146 row_mirror row_mask:0xf bank_mask:0xf bound_ctrl:1
	v_pk_fma_f32 v[198:199], v[146:147], v[190:191], v[198:199] op_sel_hi:[0,1,1] neg_lo:[1,0,0] neg_hi:[1,0,0]
	v_pk_fma_f32 v[200:201], v[146:147], v[192:193], v[200:201] op_sel_hi:[0,1,1] neg_lo:[1,0,0] neg_hi:[1,0,0]
	v_pk_fma_f32 v[138:139], v[138:139], v[194:195], v[198:199]
	v_pk_fma_f32 v[140:141], v[140:141], v[196:197], v[200:201]
	v_pk_mul_f32 v[144:145], v[138:139], v[208:209]
	v_pk_fma_f32 v[144:145], v[140:141], v[210:211], v[144:145]
	v_add_f32 v146, v144, v145
	s_nop 1
	v_add_f32_dpp v146, v146, v146 quad_perm:[1,0,3,2] row_mask:0xf bank_mask:0xf bound_ctrl:1
	v_pk_mul_f32 v[202:203], v[138:139], v[202:203]
	v_pk_fma_f32 v[202:203], v[140:141], v[204:205], v[202:203]
	v_add_f32_dpp v146, v146, v146 quad_perm:[2,3,0,1] row_mask:0xf bank_mask:0xf bound_ctrl:1
	v_add_f32 v161, v202, v203
	s_waitcnt lgkmcnt(5)
	v_add_f32_dpp v146, v146, v146 row_half_mirror row_mask:0xf bank_mask:0xf bound_ctrl:1
	v_pk_mul_f32 v[220:221], v[220:221], v[228:229] op_sel_hi:[1,0]
	v_pk_mul_f32 v[222:223], v[222:223], v[228:229] op_sel_hi:[1,0]
	v_add_f32_dpp v146, v146, v146 row_mirror row_mask:0xf bank_mask:0xf bound_ctrl:1
	v_pk_fma_f32 v[220:221], v[146:147], v[212:213], v[220:221] op_sel_hi:[0,1,1] neg_lo:[1,0,0] neg_hi:[1,0,0]
	v_pk_fma_f32 v[222:223], v[146:147], v[214:215], v[222:223] op_sel_hi:[0,1,1] neg_lo:[1,0,0] neg_hi:[1,0,0]
	v_pk_fma_f32 v[138:139], v[138:139], v[216:217], v[220:221]
	v_pk_fma_f32 v[140:141], v[140:141], v[218:219], v[222:223]
	v_pk_mul_f32 v[144:145], v[138:139], v[230:231]
	v_pk_fma_f32 v[144:145], v[140:141], v[232:233], v[144:145]
	v_add_f32 v146, v144, v145
	s_nop 1
	v_add_f32_dpp v146, v146, v146 quad_perm:[1,0,3,2] row_mask:0xf bank_mask:0xf bound_ctrl:1
	v_pk_mul_f32 v[224:225], v[138:139], v[224:225]
	v_pk_fma_f32 v[224:225], v[140:141], v[226:227], v[224:225]
	v_add_f32_dpp v146, v146, v146 quad_perm:[2,3,0,1] row_mask:0xf bank_mask:0xf bound_ctrl:1
	v_add_f32 v162, v224, v225
	s_waitcnt lgkmcnt(0)
	v_add_f32_dpp v146, v146, v146 row_half_mirror row_mask:0xf bank_mask:0xf bound_ctrl:1
	v_pk_mul_f32 v[242:243], v[242:243], v[250:251] op_sel_hi:[1,0]
	v_pk_mul_f32 v[244:245], v[244:245], v[250:251] op_sel_hi:[1,0]
	v_add_f32_dpp v146, v146, v146 row_mirror row_mask:0xf bank_mask:0xf bound_ctrl:1
	v_pk_fma_f32 v[242:243], v[146:147], v[234:235], v[242:243] op_sel_hi:[0,1,1] neg_lo:[1,0,0] neg_hi:[1,0,0]
	v_pk_fma_f32 v[244:245], v[146:147], v[236:237], v[244:245] op_sel_hi:[0,1,1] neg_lo:[1,0,0] neg_hi:[1,0,0]
	v_pk_fma_f32 v[138:139], v[138:139], v[238:239], v[242:243]
	v_pk_fma_f32 v[140:141], v[140:141], v[240:241], v[244:245]
	v_pk_mul_f32 v[246:247], v[138:139], v[246:247]
	v_pk_fma_f32 v[246:247], v[140:141], v[248:249], v[246:247]
	v_add_f32 v163, v246, v247
	s_nop 0
	v_add_f32_dpp v102, v148, v148 row_mirror row_mask:0xf bank_mask:0x3 bound_ctrl:1
	v_add_f32_dpp v102, v156, v156 row_mirror row_mask:0xf bank_mask:0xc bound_ctrl:1
	v_add_f32_dpp v103, v149, v149 row_mirror row_mask:0xf bank_mask:0x3 bound_ctrl:1
	v_add_f32_dpp v103, v157, v157 row_mirror row_mask:0xf bank_mask:0xc bound_ctrl:1
	v_add_f32_dpp v104, v150, v150 row_mirror row_mask:0xf bank_mask:0x3 bound_ctrl:1
	v_add_f32_dpp v104, v158, v158 row_mirror row_mask:0xf bank_mask:0xc bound_ctrl:1
	v_add_f32_dpp v105, v151, v151 row_mirror row_mask:0xf bank_mask:0x3 bound_ctrl:1
	v_add_f32_dpp v105, v159, v159 row_mirror row_mask:0xf bank_mask:0xc bound_ctrl:1
	v_add_f32_dpp v106, v152, v152 row_mirror row_mask:0xf bank_mask:0x3 bound_ctrl:1
	v_add_f32_dpp v106, v160, v160 row_mirror row_mask:0xf bank_mask:0xc bound_ctrl:1
	v_add_f32_dpp v107, v153, v153 row_mirror row_mask:0xf bank_mask:0x3 bound_ctrl:1
	v_add_f32_dpp v107, v161, v161 row_mirror row_mask:0xf bank_mask:0xc bound_ctrl:1
	v_add_f32_dpp v108, v154, v154 row_mirror row_mask:0xf bank_mask:0x3 bound_ctrl:1
	v_add_f32_dpp v108, v162, v162 row_mirror row_mask:0xf bank_mask:0xc bound_ctrl:1
	v_add_f32_dpp v109, v155, v155 row_mirror row_mask:0xf bank_mask:0x3 bound_ctrl:1
	v_add_f32_dpp v109, v163, v163 row_mirror row_mask:0xf bank_mask:0xc bound_ctrl:1
	v_add_f32_dpp v110, v102, v102 row_half_mirror row_mask:0xf bank_mask:0x5 bound_ctrl:1
	v_add_f32_dpp v110, v106, v106 row_half_mirror row_mask:0xf bank_mask:0xa bound_ctrl:1
	v_add_f32_dpp v111, v103, v103 row_half_mirror row_mask:0xf bank_mask:0x5 bound_ctrl:1
	v_add_f32_dpp v111, v107, v107 row_half_mirror row_mask:0xf bank_mask:0xa bound_ctrl:1
	v_add_f32_dpp v112, v104, v104 row_half_mirror row_mask:0xf bank_mask:0x5 bound_ctrl:1
	v_add_f32_dpp v112, v108, v108 row_half_mirror row_mask:0xf bank_mask:0xa bound_ctrl:1
	v_add_f32_dpp v113, v105, v105 row_half_mirror row_mask:0xf bank_mask:0x5 bound_ctrl:1
	v_add_f32_dpp v113, v109, v109 row_half_mirror row_mask:0xf bank_mask:0xa bound_ctrl:1
	s_mov_b32 vcc_lo, 0xcccccccc
	s_mov_b32 vcc_hi, 0xcccccccc
	v_cndmask_b32 v116, v112, v110, vcc
	v_cndmask_b32 v117, v113, v111, vcc
	v_cndmask_b32 v114, v110, v112, vcc
	v_cndmask_b32 v115, v111, v113, vcc
	v_add_f32_dpp v114, v116, v114 quad_perm:[2,3,0,1] row_mask:0xf bank_mask:0xf bound_ctrl:1
	v_add_f32_dpp v115, v117, v115 quad_perm:[2,3,0,1] row_mask:0xf bank_mask:0xf bound_ctrl:1
	s_mov_b32 vcc_lo, 0xaaaaaaaa
	s_mov_b32 vcc_hi, 0xaaaaaaaa
	v_cndmask_b32 v116, v115, v114, vcc
	v_cndmask_b32 v117, v114, v115, vcc
	s_nop 0
	v_add_f32_dpp v19, v116, v117 quad_perm:[1,0,3,2] row_mask:0xf bank_mask:0xf bound_ctrl:1

; #define SCAN_BAR() asm volatile("s_barrier" ::: "memory")
; __device__ __forceinline__ void scan_unit(const Ctx& C0, const float* scn, int T, int quarter, const float* S0, float* Sout, unsigned char* obase, int mode) {
;     ...
;         for (int k = 0; k < nch; ++k) {
;             const unsigned aq = (unsigned)(size_t)(C.lds + (k & 1) * SLOT_B) + 16u * (unsigned)q, av = (unsigned)(size_t)(C.lds + (k & 1) * SLOT_B) + (320u + (unsigned)irow) * 4u;
;             float osel0, osel1;
;             asm volatile(SCAN_CHUNK_ASM : "+v"(S0x), "+v"(S1x), "+v"(S2x), "+v"(S3x), "=&v"(osel0), "=&v"(osel1) : "v"(aq), "v"(av), "v"(q) : SCAN_CHUNK_CLOBBERS, "memory");
;             if (mode == 0) { *(float*)(obase + (size_t)(k * 32 + q) * UPITCH_B + rl * 4) = osel0; *(float*)(obase + (size_t)(k * 32 + 16 + q) * UPITCH_B + rl * 4) = osel1; }
;             SCAN_BAR();
;         }
;         if (mode == 0) *(f32x4*)(Sout + irow * 64 + 4 * q) = (f32x4){S0x, S1x, S2x, S3x};
	s_addc_u32 s1, s1, 0
	v_add_co_u32_e32 v16, vcc, s8, v14
	s_cmp_lg_u32 s0, 0x5600000
	s_nop 0
	v_addc_co_u32_e32 v17, vcc, 0, v15, vcc
	v_add_co_u32_e32 v14, vcc, 0xfcaa000, v14
	global_store_dword v[16:17], v18, off offset:768
	s_nop 0
	v_addc_co_u32_e32 v15, vcc, 0, v15, vcc
	global_store_dword v[14:15], v19, off offset:768
	s_barrier
	s_cbranch_scc1 .LBB0_685
	v_mov_b32_e32 v2, v138
	v_mov_b32_e32 v13, v139
	v_mov_b32_e32 v12, v140
	v_mov_b32_e32 v8, v141
	v_readlane_b32 s0, v255, 46
	s_add_i32 s0, s3, s0
	s_ashr_i32 s1, s0, 31
	s_lshl_b64 s[0:1], s[0:1], 17
	v_readlane_b32 s3, v253, 26
	s_add_u32 s0, s3, s0
	v_readlane_b32 s3, v253, 27
	s_addc_u32 s1, s3, s1
	s_lshl_b32 s2, s2, 14
	s_add_u32 s0, s0, s2
	s_addc_u32 s1, s1, 0
	v_lshlrev_b32_e32 v0, 8, v0
	v_lshl_add_u64 v[6:7], s[0:1], 0, v[0:1]
	v_mov_b32_e32 v5, v1
	v_lshl_add_u64 v[6:7], v[6:7], 0, v[4:5]
	v_mov_b32_e32 v3, v13
	v_mov_b32_e32 v4, v12
	v_mov_b32_e32 v5, v8
	global_store_dwordx4 v[6:7], v[2:5], off
